# v69 + nt on the read-once epilogue loads (g_a / t2 in the merge epilogues, g_b in the t2 fast path)
# baseline (speedup 1.0000x reference)
.LBB0_645:
	v_readlane_b32 s12, v255, 0
	v_or_b32_e32 v130, s54, v143
	v_lshl_or_b32 v131, v142, 11, s55
	s_lshl_b32 s10, s20, 9
	v_readlane_b32 s13, v255, 1
	v_readlane_b32 s14, v255, 2
	v_readlane_b32 s15, v255, 3
	v_readlane_b32 s16, v255, 4
	v_readlane_b32 s17, v255, 5
	v_or_b32_e32 v128, v131, v130
	s_or_b32 s10, s21, s10
	v_readlane_b32 s18, v255, 6
	v_readlane_b32 s19, v255, 7
	s_mov_b64 s[12:13], s[16:17]
	v_add_u32_e32 v128, s10, v128
	s_mov_b64 s[14:15], s[18:19]
	v_mov_b32_e32 v220, v128
	v_add_u32_e32 v221, 0x8000, v128
	v_add_u32_e32 v222, 0x10000, v128
	v_add_u32_e32 v223, 0x18000, v128
	v_add_u32_e32 v224, 0x40000, v128
	v_add_u32_e32 v225, 0x48000, v128
	v_add_u32_e32 v226, 0x50000, v128
	v_add_u32_e32 v227, 0x58000, v128
	global_load_dwordx4 v[156:159], v220, s[24:25] nt
	global_load_dwordx4 v[160:163], v220, s[14:15] nt
	global_load_dwordx4 v[164:167], v220, s[24:25] offset:256 nt
	global_load_dwordx4 v[168:171], v220, s[14:15] offset:256 nt
	global_load_dwordx4 v[172:175], v221, s[24:25] nt
	global_load_dwordx4 v[176:179], v221, s[14:15] nt
	global_load_dwordx4 v[180:183], v221, s[24:25] offset:256 nt
	global_load_dwordx4 v[184:187], v221, s[14:15] offset:256 nt
	global_load_dwordx4 v[188:191], v222, s[24:25] nt
	global_load_dwordx4 v[192:195], v222, s[14:15] nt
	global_load_dwordx4 v[196:199], v222, s[24:25] offset:256 nt
	global_load_dwordx4 v[200:203], v222, s[14:15] offset:256 nt
	global_load_dwordx4 v[204:207], v223, s[24:25] nt
	global_load_dwordx4 v[208:211], v223, s[14:15] nt
	global_load_dwordx4 v[212:215], v223, s[24:25] offset:256 nt
	global_load_dwordx4 v[216:219], v223, s[14:15] offset:256 nt
	s_waitcnt vmcnt(14)
	v_cvt_f32_f16_e32 v228, v156
	v_cvt_f32_f16_sdwa v229, v156 dst_sel:DWORD dst_unused:UNUSED_PAD src0_sel:WORD_1
	v_cvt_f32_f16_e32 v230, v157
	v_cvt_f32_f16_sdwa v231, v157 dst_sel:DWORD dst_unused:UNUSED_PAD src0_sel:WORD_1
	v_cvt_f32_f16_e32 v232, v158
	v_cvt_f32_f16_sdwa v233, v158 dst_sel:DWORD dst_unused:UNUSED_PAD src0_sel:WORD_1
	v_cvt_f32_f16_e32 v234, v159
	v_cvt_f32_f16_sdwa v235, v159 dst_sel:DWORD dst_unused:UNUSED_PAD src0_sel:WORD_1
	v_cvt_f32_f16_e32 v236, v160
	v_cvt_f32_f16_sdwa v237, v160 dst_sel:DWORD dst_unused:UNUSED_PAD src0_sel:WORD_1
	v_cvt_f32_f16_e32 v238, v161
	v_cvt_f32_f16_sdwa v239, v161 dst_sel:DWORD dst_unused:UNUSED_PAD src0_sel:WORD_1
	v_cvt_f32_f16_e32 v240, v162
	v_cvt_f32_f16_sdwa v241, v162 dst_sel:DWORD dst_unused:UNUSED_PAD src0_sel:WORD_1
	v_cvt_f32_f16_e32 v242, v163
	v_cvt_f32_f16_sdwa v243, v163 dst_sel:DWORD dst_unused:UNUSED_PAD src0_sel:WORD_1
	v_pk_fma_f32 v[124:125], v[124:125], v[236:237], v[228:229]
	v_pk_fma_f32 v[126:127], v[126:127], v[238:239], v[230:231]
	v_pk_fma_f32 v[120:121], v[120:121], v[240:241], v[232:233]
	v_pk_fma_f32 v[122:123], v[122:123], v[242:243], v[234:235]
	v_cvt_pk_f16_f32 v156, v124, v125
	v_cvt_pk_f16_f32 v157, v126, v127
	v_cvt_pk_f16_f32 v158, v120, v121
	v_cvt_pk_f16_f32 v159, v122, v123
	global_store_dwordx4 v220, v[156:159], s[22:23] sc1
	s_nop 1
	global_load_dwordx4 v[156:159], v224, s[24:25] nt
	global_load_dwordx4 v[160:163], v224, s[14:15] nt
	s_waitcnt vmcnt(15)
	v_cvt_f32_f16_e32 v228, v164
	v_cvt_f32_f16_sdwa v229, v164 dst_sel:DWORD dst_unused:UNUSED_PAD src0_sel:WORD_1
	v_cvt_f32_f16_e32 v230, v165
	v_cvt_f32_f16_sdwa v231, v165 dst_sel:DWORD dst_unused:UNUSED_PAD src0_sel:WORD_1
	v_cvt_f32_f16_e32 v232, v166
	v_cvt_f32_f16_sdwa v233, v166 dst_sel:DWORD dst_unused:UNUSED_PAD src0_sel:WORD_1
	v_cvt_f32_f16_e32 v234, v167
	v_cvt_f32_f16_sdwa v235, v167 dst_sel:DWORD dst_unused:UNUSED_PAD src0_sel:WORD_1
	v_cvt_f32_f16_e32 v236, v168
	v_cvt_f32_f16_sdwa v237, v168 dst_sel:DWORD dst_unused:UNUSED_PAD src0_sel:WORD_1
	v_cvt_f32_f16_e32 v238, v169
	v_cvt_f32_f16_sdwa v239, v169 dst_sel:DWORD dst_unused:UNUSED_PAD src0_sel:WORD_1
	v_cvt_f32_f16_e32 v240, v170
	v_cvt_f32_f16_sdwa v241, v170 dst_sel:DWORD dst_unused:UNUSED_PAD src0_sel:WORD_1
	v_cvt_f32_f16_e32 v242, v171
	v_cvt_f32_f16_sdwa v243, v171 dst_sel:DWORD dst_unused:UNUSED_PAD src0_sel:WORD_1
	v_pk_fma_f32 v[116:117], v[116:117], v[236:237], v[228:229]
	v_pk_fma_f32 v[118:119], v[118:119], v[238:239], v[230:231]
	v_pk_fma_f32 v[112:113], v[112:113], v[240:241], v[232:233]
	v_pk_fma_f32 v[114:115], v[114:115], v[242:243], v[234:235]
	v_cvt_pk_f16_f32 v164, v116, v117
	v_cvt_pk_f16_f32 v165, v118, v119
	v_cvt_pk_f16_f32 v166, v112, v113
	v_cvt_pk_f16_f32 v167, v114, v115
	global_store_dwordx4 v220, v[164:167], s[22:23] offset:256 sc1
	s_nop 1
	global_load_dwordx4 v[164:167], v224, s[24:25] offset:256 nt
	global_load_dwordx4 v[168:171], v224, s[14:15] offset:256 nt
	s_waitcnt vmcnt(16)
	v_cvt_f32_f16_e32 v228, v172
	v_cvt_f32_f16_sdwa v229, v172 dst_sel:DWORD dst_unused:UNUSED_PAD src0_sel:WORD_1
	v_cvt_f32_f16_e32 v230, v173
	v_cvt_f32_f16_sdwa v231, v173 dst_sel:DWORD dst_unused:UNUSED_PAD src0_sel:WORD_1
	v_cvt_f32_f16_e32 v232, v174
	v_cvt_f32_f16_sdwa v233, v174 dst_sel:DWORD dst_unused:UNUSED_PAD src0_sel:WORD_1
	v_cvt_f32_f16_e32 v234, v175
	v_cvt_f32_f16_sdwa v235, v175 dst_sel:DWORD dst_unused:UNUSED_PAD src0_sel:WORD_1
	v_cvt_f32_f16_e32 v236, v176
	v_cvt_f32_f16_sdwa v237, v176 dst_sel:DWORD dst_unused:UNUSED_PAD src0_sel:WORD_1
	v_cvt_f32_f16_e32 v238, v177
	v_cvt_f32_f16_sdwa v239, v177 dst_sel:DWORD dst_unused:UNUSED_PAD src0_sel:WORD_1
	v_cvt_f32_f16_e32 v240, v178
	v_cvt_f32_f16_sdwa v241, v178 dst_sel:DWORD dst_unused:UNUSED_PAD src0_sel:WORD_1
	v_cvt_f32_f16_e32 v242, v179
	v_cvt_f32_f16_sdwa v243, v179 dst_sel:DWORD dst_unused:UNUSED_PAD src0_sel:WORD_1
	v_pk_fma_f32 v[108:109], v[108:109], v[236:237], v[228:229]
	v_pk_fma_f32 v[110:111], v[110:111], v[238:239], v[230:231]
	v_pk_fma_f32 v[104:105], v[104:105], v[240:241], v[232:233]
	v_pk_fma_f32 v[106:107], v[106:107], v[242:243], v[234:235]
	v_cvt_pk_f16_f32 v172, v108, v109
	v_cvt_pk_f16_f32 v173, v110, v111
	v_cvt_pk_f16_f32 v174, v104, v105
	v_cvt_pk_f16_f32 v175, v106, v107
	global_store_dwordx4 v221, v[172:175], s[22:23] sc1
	s_nop 1
	global_load_dwordx4 v[172:175], v225, s[24:25] nt
	global_load_dwordx4 v[176:179], v225, s[14:15] nt
	s_waitcnt vmcnt(17)
	v_cvt_f32_f16_e32 v228, v180
	v_cvt_f32_f16_sdwa v229, v180 dst_sel:DWORD dst_unused:UNUSED_PAD src0_sel:WORD_1
	v_cvt_f32_f16_e32 v230, v181
	v_cvt_f32_f16_sdwa v231, v181 dst_sel:DWORD dst_unused:UNUSED_PAD src0_sel:WORD_1
	v_cvt_f32_f16_e32 v232, v182
	v_cvt_f32_f16_sdwa v233, v182 dst_sel:DWORD dst_unused:UNUSED_PAD src0_sel:WORD_1
	v_cvt_f32_f16_e32 v234, v183
	v_cvt_f32_f16_sdwa v235, v183 dst_sel:DWORD dst_unused:UNUSED_PAD src0_sel:WORD_1
	v_cvt_f32_f16_e32 v236, v184
	v_cvt_f32_f16_sdwa v237, v184 dst_sel:DWORD dst_unused:UNUSED_PAD src0_sel:WORD_1
	v_cvt_f32_f16_e32 v238, v185
	v_cvt_f32_f16_sdwa v239, v185 dst_sel:DWORD dst_unused:UNUSED_PAD src0_sel:WORD_1
	v_cvt_f32_f16_e32 v240, v186
	v_cvt_f32_f16_sdwa v241, v186 dst_sel:DWORD dst_unused:UNUSED_PAD src0_sel:WORD_1
	v_cvt_f32_f16_e32 v242, v187
	v_cvt_f32_f16_sdwa v243, v187 dst_sel:DWORD dst_unused:UNUSED_PAD src0_sel:WORD_1
	v_pk_fma_f32 v[100:101], v[100:101], v[236:237], v[228:229]
	v_pk_fma_f32 v[102:103], v[102:103], v[238:239], v[230:231]
	v_pk_fma_f32 v[96:97], v[96:97], v[240:241], v[232:233]
	v_pk_fma_f32 v[98:99], v[98:99], v[242:243], v[234:235]
	v_cvt_pk_f16_f32 v180, v100, v101
	v_cvt_pk_f16_f32 v181, v102, v103
	v_cvt_pk_f16_f32 v182, v96, v97
	v_cvt_pk_f16_f32 v183, v98, v99
	global_store_dwordx4 v221, v[180:183], s[22:23] offset:256 sc1
	s_nop 1
	global_load_dwordx4 v[180:183], v225, s[24:25] offset:256 nt
	global_load_dwordx4 v[184:187], v225, s[14:15] offset:256 nt
	s_waitcnt vmcnt(18)
	v_cvt_f32_f16_e32 v228, v188
	v_cvt_f32_f16_sdwa v229, v188 dst_sel:DWORD dst_unused:UNUSED_PAD src0_sel:WORD_1
	v_cvt_f32_f16_e32 v230, v189
	v_cvt_f32_f16_sdwa v231, v189 dst_sel:DWORD dst_unused:UNUSED_PAD src0_sel:WORD_1
	v_cvt_f32_f16_e32 v232, v190
	v_cvt_f32_f16_sdwa v233, v190 dst_sel:DWORD dst_unused:UNUSED_PAD src0_sel:WORD_1
	v_cvt_f32_f16_e32 v234, v191
	v_cvt_f32_f16_sdwa v235, v191 dst_sel:DWORD dst_unused:UNUSED_PAD src0_sel:WORD_1
	v_cvt_f32_f16_e32 v236, v192
	v_cvt_f32_f16_sdwa v237, v192 dst_sel:DWORD dst_unused:UNUSED_PAD src0_sel:WORD_1
	v_cvt_f32_f16_e32 v238, v193
	v_cvt_f32_f16_sdwa v239, v193 dst_sel:DWORD dst_unused:UNUSED_PAD src0_sel:WORD_1
	v_cvt_f32_f16_e32 v240, v194
	v_cvt_f32_f16_sdwa v241, v194 dst_sel:DWORD dst_unused:UNUSED_PAD src0_sel:WORD_1
	v_cvt_f32_f16_e32 v242, v195
	v_cvt_f32_f16_sdwa v243, v195 dst_sel:DWORD dst_unused:UNUSED_PAD src0_sel:WORD_1
	v_pk_fma_f32 v[92:93], v[92:93], v[236:237], v[228:229]
	v_pk_fma_f32 v[94:95], v[94:95], v[238:239], v[230:231]
	v_pk_fma_f32 v[88:89], v[88:89], v[240:241], v[232:233]
	v_pk_fma_f32 v[90:91], v[90:91], v[242:243], v[234:235]
	v_cvt_pk_f16_f32 v188, v92, v93
	v_cvt_pk_f16_f32 v189, v94, v95
	v_cvt_pk_f16_f32 v190, v88, v89
	v_cvt_pk_f16_f32 v191, v90, v91
	global_store_dwordx4 v222, v[188:191], s[22:23] sc1
	s_nop 1
	global_load_dwordx4 v[188:191], v226, s[24:25] nt
	global_load_dwordx4 v[192:195], v226, s[14:15] nt
	s_waitcnt vmcnt(19)
	v_cvt_f32_f16_e32 v228, v196
	v_cvt_f32_f16_sdwa v229, v196 dst_sel:DWORD dst_unused:UNUSED_PAD src0_sel:WORD_1
	v_cvt_f32_f16_e32 v230, v197
	v_cvt_f32_f16_sdwa v231, v197 dst_sel:DWORD dst_unused:UNUSED_PAD src0_sel:WORD_1
	v_cvt_f32_f16_e32 v232, v198
	v_cvt_f32_f16_sdwa v233, v198 dst_sel:DWORD dst_unused:UNUSED_PAD src0_sel:WORD_1
	v_cvt_f32_f16_e32 v234, v199
	v_cvt_f32_f16_sdwa v235, v199 dst_sel:DWORD dst_unused:UNUSED_PAD src0_sel:WORD_1
	v_cvt_f32_f16_e32 v236, v200
	v_cvt_f32_f16_sdwa v237, v200 dst_sel:DWORD dst_unused:UNUSED_PAD src0_sel:WORD_1
	v_cvt_f32_f16_e32 v238, v201
	v_cvt_f32_f16_sdwa v239, v201 dst_sel:DWORD dst_unused:UNUSED_PAD src0_sel:WORD_1
	v_cvt_f32_f16_e32 v240, v202
	v_cvt_f32_f16_sdwa v241, v202 dst_sel:DWORD dst_unused:UNUSED_PAD src0_sel:WORD_1
	v_cvt_f32_f16_e32 v242, v203
	v_cvt_f32_f16_sdwa v243, v203 dst_sel:DWORD dst_unused:UNUSED_PAD src0_sel:WORD_1
	v_pk_fma_f32 v[84:85], v[84:85], v[236:237], v[228:229]
	v_pk_fma_f32 v[86:87], v[86:87], v[238:239], v[230:231]
	v_pk_fma_f32 v[80:81], v[80:81], v[240:241], v[232:233]
	v_pk_fma_f32 v[82:83], v[82:83], v[242:243], v[234:235]
	v_cvt_pk_f16_f32 v196, v84, v85
	v_cvt_pk_f16_f32 v197, v86, v87
	v_cvt_pk_f16_f32 v198, v80, v81
	v_cvt_pk_f16_f32 v199, v82, v83
	global_store_dwordx4 v222, v[196:199], s[22:23] offset:256 sc1
	s_nop 1
	global_load_dwordx4 v[196:199], v226, s[24:25] offset:256 nt
	global_load_dwordx4 v[200:203], v226, s[14:15] offset:256 nt
	s_waitcnt vmcnt(20)
	v_cvt_f32_f16_e32 v228, v204
	v_cvt_f32_f16_sdwa v229, v204 dst_sel:DWORD dst_unused:UNUSED_PAD src0_sel:WORD_1
	v_cvt_f32_f16_e32 v230, v205
	v_cvt_f32_f16_sdwa v231, v205 dst_sel:DWORD dst_unused:UNUSED_PAD src0_sel:WORD_1
	v_cvt_f32_f16_e32 v232, v206
	v_cvt_f32_f16_sdwa v233, v206 dst_sel:DWORD dst_unused:UNUSED_PAD src0_sel:WORD_1
	v_cvt_f32_f16_e32 v234, v207
	v_cvt_f32_f16_sdwa v235, v207 dst_sel:DWORD dst_unused:UNUSED_PAD src0_sel:WORD_1
	v_cvt_f32_f16_e32 v236, v208
	v_cvt_f32_f16_sdwa v237, v208 dst_sel:DWORD dst_unused:UNUSED_PAD src0_sel:WORD_1
	v_cvt_f32_f16_e32 v238, v209
	v_cvt_f32_f16_sdwa v239, v209 dst_sel:DWORD dst_unused:UNUSED_PAD src0_sel:WORD_1
	v_cvt_f32_f16_e32 v240, v210
	v_cvt_f32_f16_sdwa v241, v210 dst_sel:DWORD dst_unused:UNUSED_PAD src0_sel:WORD_1
	v_cvt_f32_f16_e32 v242, v211
	v_cvt_f32_f16_sdwa v243, v211 dst_sel:DWORD dst_unused:UNUSED_PAD src0_sel:WORD_1
	v_pk_fma_f32 v[76:77], v[76:77], v[236:237], v[228:229]
	v_pk_fma_f32 v[78:79], v[78:79], v[238:239], v[230:231]
	v_pk_fma_f32 v[72:73], v[72:73], v[240:241], v[232:233]
	v_pk_fma_f32 v[74:75], v[74:75], v[242:243], v[234:235]
	v_cvt_pk_f16_f32 v204, v76, v77
	v_cvt_pk_f16_f32 v205, v78, v79
	v_cvt_pk_f16_f32 v206, v72, v73
	v_cvt_pk_f16_f32 v207, v74, v75
	global_store_dwordx4 v223, v[204:207], s[22:23] sc1
	s_nop 1
	global_load_dwordx4 v[204:207], v227, s[24:25] nt
	global_load_dwordx4 v[208:211], v227, s[14:15] nt
	s_waitcnt vmcnt(21)
	v_cvt_f32_f16_e32 v228, v212
	v_cvt_f32_f16_sdwa v229, v212 dst_sel:DWORD dst_unused:UNUSED_PAD src0_sel:WORD_1
	v_cvt_f32_f16_e32 v230, v213
	v_cvt_f32_f16_sdwa v231, v213 dst_sel:DWORD dst_unused:UNUSED_PAD src0_sel:WORD_1
	v_cvt_f32_f16_e32 v232, v214
	v_cvt_f32_f16_sdwa v233, v214 dst_sel:DWORD dst_unused:UNUSED_PAD src0_sel:WORD_1
	v_cvt_f32_f16_e32 v234, v215
	v_cvt_f32_f16_sdwa v235, v215 dst_sel:DWORD dst_unused:UNUSED_PAD src0_sel:WORD_1
	v_cvt_f32_f16_e32 v236, v216
	v_cvt_f32_f16_sdwa v237, v216 dst_sel:DWORD dst_unused:UNUSED_PAD src0_sel:WORD_1
	v_cvt_f32_f16_e32 v238, v217
	v_cvt_f32_f16_sdwa v239, v217 dst_sel:DWORD dst_unused:UNUSED_PAD src0_sel:WORD_1
	v_cvt_f32_f16_e32 v240, v218
	v_cvt_f32_f16_sdwa v241, v218 dst_sel:DWORD dst_unused:UNUSED_PAD src0_sel:WORD_1
	v_cvt_f32_f16_e32 v242, v219
	v_cvt_f32_f16_sdwa v243, v219 dst_sel:DWORD dst_unused:UNUSED_PAD src0_sel:WORD_1
	v_pk_fma_f32 v[68:69], v[68:69], v[236:237], v[228:229]
	v_pk_fma_f32 v[70:71], v[70:71], v[238:239], v[230:231]
	v_pk_fma_f32 v[64:65], v[64:65], v[240:241], v[232:233]
	v_pk_fma_f32 v[66:67], v[66:67], v[242:243], v[234:235]
	v_cvt_pk_f16_f32 v212, v68, v69
	v_cvt_pk_f16_f32 v213, v70, v71
	v_cvt_pk_f16_f32 v214, v64, v65
	v_cvt_pk_f16_f32 v215, v66, v67
	global_store_dwordx4 v223, v[212:215], s[22:23] offset:256 sc1
	s_nop 1
	global_load_dwordx4 v[212:215], v227, s[24:25] offset:256 nt
	global_load_dwordx4 v[216:219], v227, s[14:15] offset:256 nt
	s_waitcnt vmcnt(21)
	v_cvt_f32_f16_e32 v228, v156
	v_cvt_f32_f16_sdwa v229, v156 dst_sel:DWORD dst_unused:UNUSED_PAD src0_sel:WORD_1
	v_cvt_f32_f16_e32 v230, v157
	v_cvt_f32_f16_sdwa v231, v157 dst_sel:DWORD dst_unused:UNUSED_PAD src0_sel:WORD_1
	v_cvt_f32_f16_e32 v232, v158
	v_cvt_f32_f16_sdwa v233, v158 dst_sel:DWORD dst_unused:UNUSED_PAD src0_sel:WORD_1
	v_cvt_f32_f16_e32 v234, v159
	v_cvt_f32_f16_sdwa v235, v159 dst_sel:DWORD dst_unused:UNUSED_PAD src0_sel:WORD_1
	v_cvt_f32_f16_e32 v236, v160
	v_cvt_f32_f16_sdwa v237, v160 dst_sel:DWORD dst_unused:UNUSED_PAD src0_sel:WORD_1
	v_cvt_f32_f16_e32 v238, v161
	v_cvt_f32_f16_sdwa v239, v161 dst_sel:DWORD dst_unused:UNUSED_PAD src0_sel:WORD_1
	v_cvt_f32_f16_e32 v240, v162
	v_cvt_f32_f16_sdwa v241, v162 dst_sel:DWORD dst_unused:UNUSED_PAD src0_sel:WORD_1
	v_cvt_f32_f16_e32 v242, v163
	v_cvt_f32_f16_sdwa v243, v163 dst_sel:DWORD dst_unused:UNUSED_PAD src0_sel:WORD_1
	v_pk_fma_f32 v[60:61], v[60:61], v[236:237], v[228:229]
	v_pk_fma_f32 v[62:63], v[62:63], v[238:239], v[230:231]
	v_pk_fma_f32 v[56:57], v[56:57], v[240:241], v[232:233]
	v_pk_fma_f32 v[58:59], v[58:59], v[242:243], v[234:235]
	v_cvt_pk_f16_f32 v156, v60, v61
	v_cvt_pk_f16_f32 v157, v62, v63
	v_cvt_pk_f16_f32 v158, v56, v57
	v_cvt_pk_f16_f32 v159, v58, v59
	global_store_dwordx4 v224, v[156:159], s[22:23] sc1
	s_nop 1
	s_waitcnt vmcnt(19)
	v_cvt_f32_f16_e32 v228, v164
	v_cvt_f32_f16_sdwa v229, v164 dst_sel:DWORD dst_unused:UNUSED_PAD src0_sel:WORD_1
	v_cvt_f32_f16_e32 v230, v165
	v_cvt_f32_f16_sdwa v231, v165 dst_sel:DWORD dst_unused:UNUSED_PAD src0_sel:WORD_1
	v_cvt_f32_f16_e32 v232, v166
	v_cvt_f32_f16_sdwa v233, v166 dst_sel:DWORD dst_unused:UNUSED_PAD src0_sel:WORD_1
	v_cvt_f32_f16_e32 v234, v167
	v_cvt_f32_f16_sdwa v235, v167 dst_sel:DWORD dst_unused:UNUSED_PAD src0_sel:WORD_1
	v_cvt_f32_f16_e32 v236, v168
	v_cvt_f32_f16_sdwa v237, v168 dst_sel:DWORD dst_unused:UNUSED_PAD src0_sel:WORD_1
	v_cvt_f32_f16_e32 v238, v169
	v_cvt_f32_f16_sdwa v239, v169 dst_sel:DWORD dst_unused:UNUSED_PAD src0_sel:WORD_1
	v_cvt_f32_f16_e32 v240, v170
	v_cvt_f32_f16_sdwa v241, v170 dst_sel:DWORD dst_unused:UNUSED_PAD src0_sel:WORD_1
	v_cvt_f32_f16_e32 v242, v171
	v_cvt_f32_f16_sdwa v243, v171 dst_sel:DWORD dst_unused:UNUSED_PAD src0_sel:WORD_1
	v_pk_fma_f32 v[52:53], v[52:53], v[236:237], v[228:229]
	v_pk_fma_f32 v[54:55], v[54:55], v[238:239], v[230:231]
	v_pk_fma_f32 v[48:49], v[48:49], v[240:241], v[232:233]
	v_pk_fma_f32 v[50:51], v[50:51], v[242:243], v[234:235]
	v_cvt_pk_f16_f32 v164, v52, v53
	v_cvt_pk_f16_f32 v165, v54, v55
	v_cvt_pk_f16_f32 v166, v48, v49
	v_cvt_pk_f16_f32 v167, v50, v51
	global_store_dwordx4 v224, v[164:167], s[22:23] offset:256 sc1
	s_nop 1
	s_waitcnt vmcnt(17)
	v_cvt_f32_f16_e32 v228, v172
	v_cvt_f32_f16_sdwa v229, v172 dst_sel:DWORD dst_unused:UNUSED_PAD src0_sel:WORD_1
	v_cvt_f32_f16_e32 v230, v173
	v_cvt_f32_f16_sdwa v231, v173 dst_sel:DWORD dst_unused:UNUSED_PAD src0_sel:WORD_1
	v_cvt_f32_f16_e32 v232, v174
	v_cvt_f32_f16_sdwa v233, v174 dst_sel:DWORD dst_unused:UNUSED_PAD src0_sel:WORD_1
	v_cvt_f32_f16_e32 v234, v175
	v_cvt_f32_f16_sdwa v235, v175 dst_sel:DWORD dst_unused:UNUSED_PAD src0_sel:WORD_1
	v_cvt_f32_f16_e32 v236, v176
	v_cvt_f32_f16_sdwa v237, v176 dst_sel:DWORD dst_unused:UNUSED_PAD src0_sel:WORD_1
	v_cvt_f32_f16_e32 v238, v177
	v_cvt_f32_f16_sdwa v239, v177 dst_sel:DWORD dst_unused:UNUSED_PAD src0_sel:WORD_1
	v_cvt_f32_f16_e32 v240, v178
	v_cvt_f32_f16_sdwa v241, v178 dst_sel:DWORD dst_unused:UNUSED_PAD src0_sel:WORD_1
	v_cvt_f32_f16_e32 v242, v179
	v_cvt_f32_f16_sdwa v243, v179 dst_sel:DWORD dst_unused:UNUSED_PAD src0_sel:WORD_1
	v_pk_fma_f32 v[44:45], v[44:45], v[236:237], v[228:229]
	v_pk_fma_f32 v[46:47], v[46:47], v[238:239], v[230:231]
	v_pk_fma_f32 v[40:41], v[40:41], v[240:241], v[232:233]
	v_pk_fma_f32 v[42:43], v[42:43], v[242:243], v[234:235]
	v_cvt_pk_f16_f32 v172, v44, v45
	v_cvt_pk_f16_f32 v173, v46, v47
	v_cvt_pk_f16_f32 v174, v40, v41
	v_cvt_pk_f16_f32 v175, v42, v43
	global_store_dwordx4 v225, v[172:175], s[22:23] sc1
	s_nop 1
	s_waitcnt vmcnt(15)
	v_cvt_f32_f16_e32 v228, v180
	v_cvt_f32_f16_sdwa v229, v180 dst_sel:DWORD dst_unused:UNUSED_PAD src0_sel:WORD_1
	v_cvt_f32_f16_e32 v230, v181
	v_cvt_f32_f16_sdwa v231, v181 dst_sel:DWORD dst_unused:UNUSED_PAD src0_sel:WORD_1
	v_cvt_f32_f16_e32 v232, v182
	v_cvt_f32_f16_sdwa v233, v182 dst_sel:DWORD dst_unused:UNUSED_PAD src0_sel:WORD_1
	v_cvt_f32_f16_e32 v234, v183
	v_cvt_f32_f16_sdwa v235, v183 dst_sel:DWORD dst_unused:UNUSED_PAD src0_sel:WORD_1
	v_cvt_f32_f16_e32 v236, v184
	v_cvt_f32_f16_sdwa v237, v184 dst_sel:DWORD dst_unused:UNUSED_PAD src0_sel:WORD_1
	v_cvt_f32_f16_e32 v238, v185
	v_cvt_f32_f16_sdwa v239, v185 dst_sel:DWORD dst_unused:UNUSED_PAD src0_sel:WORD_1
	v_cvt_f32_f16_e32 v240, v186
	v_cvt_f32_f16_sdwa v241, v186 dst_sel:DWORD dst_unused:UNUSED_PAD src0_sel:WORD_1
	v_cvt_f32_f16_e32 v242, v187
	v_cvt_f32_f16_sdwa v243, v187 dst_sel:DWORD dst_unused:UNUSED_PAD src0_sel:WORD_1
	v_pk_fma_f32 v[36:37], v[36:37], v[236:237], v[228:229]
	v_pk_fma_f32 v[38:39], v[38:39], v[238:239], v[230:231]
	v_pk_fma_f32 v[32:33], v[32:33], v[240:241], v[232:233]
	v_pk_fma_f32 v[34:35], v[34:35], v[242:243], v[234:235]
	v_cvt_pk_f16_f32 v180, v36, v37
	v_cvt_pk_f16_f32 v181, v38, v39
	v_cvt_pk_f16_f32 v182, v32, v33
	v_cvt_pk_f16_f32 v183, v34, v35
	global_store_dwordx4 v225, v[180:183], s[22:23] offset:256 sc1
	s_nop 1
	s_waitcnt vmcnt(13)
	v_cvt_f32_f16_e32 v228, v188
	v_cvt_f32_f16_sdwa v229, v188 dst_sel:DWORD dst_unused:UNUSED_PAD src0_sel:WORD_1
	v_cvt_f32_f16_e32 v230, v189
	v_cvt_f32_f16_sdwa v231, v189 dst_sel:DWORD dst_unused:UNUSED_PAD src0_sel:WORD_1
	v_cvt_f32_f16_e32 v232, v190
	v_cvt_f32_f16_sdwa v233, v190 dst_sel:DWORD dst_unused:UNUSED_PAD src0_sel:WORD_1
	v_cvt_f32_f16_e32 v234, v191
	v_cvt_f32_f16_sdwa v235, v191 dst_sel:DWORD dst_unused:UNUSED_PAD src0_sel:WORD_1
	v_cvt_f32_f16_e32 v236, v192
	v_cvt_f32_f16_sdwa v237, v192 dst_sel:DWORD dst_unused:UNUSED_PAD src0_sel:WORD_1
	v_cvt_f32_f16_e32 v238, v193
	v_cvt_f32_f16_sdwa v239, v193 dst_sel:DWORD dst_unused:UNUSED_PAD src0_sel:WORD_1
	v_cvt_f32_f16_e32 v240, v194
	v_cvt_f32_f16_sdwa v241, v194 dst_sel:DWORD dst_unused:UNUSED_PAD src0_sel:WORD_1
	v_cvt_f32_f16_e32 v242, v195
	v_cvt_f32_f16_sdwa v243, v195 dst_sel:DWORD dst_unused:UNUSED_PAD src0_sel:WORD_1
	v_pk_fma_f32 v[28:29], v[28:29], v[236:237], v[228:229]
	v_pk_fma_f32 v[30:31], v[30:31], v[238:239], v[230:231]
	v_pk_fma_f32 v[24:25], v[24:25], v[240:241], v[232:233]
	v_pk_fma_f32 v[26:27], v[26:27], v[242:243], v[234:235]
	v_cvt_pk_f16_f32 v188, v28, v29
	v_cvt_pk_f16_f32 v189, v30, v31
	v_cvt_pk_f16_f32 v190, v24, v25
	v_cvt_pk_f16_f32 v191, v26, v27
	global_store_dwordx4 v226, v[188:191], s[22:23] sc1
	s_nop 1
	s_waitcnt vmcnt(11)
	v_cvt_f32_f16_e32 v228, v196
	v_cvt_f32_f16_sdwa v229, v196 dst_sel:DWORD dst_unused:UNUSED_PAD src0_sel:WORD_1
	v_cvt_f32_f16_e32 v230, v197
	v_cvt_f32_f16_sdwa v231, v197 dst_sel:DWORD dst_unused:UNUSED_PAD src0_sel:WORD_1
	v_cvt_f32_f16_e32 v232, v198
	v_cvt_f32_f16_sdwa v233, v198 dst_sel:DWORD dst_unused:UNUSED_PAD src0_sel:WORD_1
	v_cvt_f32_f16_e32 v234, v199
	v_cvt_f32_f16_sdwa v235, v199 dst_sel:DWORD dst_unused:UNUSED_PAD src0_sel:WORD_1
	v_cvt_f32_f16_e32 v236, v200
	v_cvt_f32_f16_sdwa v237, v200 dst_sel:DWORD dst_unused:UNUSED_PAD src0_sel:WORD_1
	v_cvt_f32_f16_e32 v238, v201
	v_cvt_f32_f16_sdwa v239, v201 dst_sel:DWORD dst_unused:UNUSED_PAD src0_sel:WORD_1
	v_cvt_f32_f16_e32 v240, v202
	v_cvt_f32_f16_sdwa v241, v202 dst_sel:DWORD dst_unused:UNUSED_PAD src0_sel:WORD_1
	v_cvt_f32_f16_e32 v242, v203
	v_cvt_f32_f16_sdwa v243, v203 dst_sel:DWORD dst_unused:UNUSED_PAD src0_sel:WORD_1
	v_pk_fma_f32 v[20:21], v[20:21], v[236:237], v[228:229]
	v_pk_fma_f32 v[22:23], v[22:23], v[238:239], v[230:231]
	v_pk_fma_f32 v[16:17], v[16:17], v[240:241], v[232:233]
	v_pk_fma_f32 v[18:19], v[18:19], v[242:243], v[234:235]
	v_cvt_pk_f16_f32 v196, v20, v21
	v_cvt_pk_f16_f32 v197, v22, v23
	v_cvt_pk_f16_f32 v198, v16, v17
	v_cvt_pk_f16_f32 v199, v18, v19
	global_store_dwordx4 v226, v[196:199], s[22:23] offset:256 sc1
	s_nop 1
	s_waitcnt vmcnt(9)
	v_cvt_f32_f16_e32 v228, v204
	v_cvt_f32_f16_sdwa v229, v204 dst_sel:DWORD dst_unused:UNUSED_PAD src0_sel:WORD_1
	v_cvt_f32_f16_e32 v230, v205
	v_cvt_f32_f16_sdwa v231, v205 dst_sel:DWORD dst_unused:UNUSED_PAD src0_sel:WORD_1
	v_cvt_f32_f16_e32 v232, v206
	v_cvt_f32_f16_sdwa v233, v206 dst_sel:DWORD dst_unused:UNUSED_PAD src0_sel:WORD_1
	v_cvt_f32_f16_e32 v234, v207
	v_cvt_f32_f16_sdwa v235, v207 dst_sel:DWORD dst_unused:UNUSED_PAD src0_sel:WORD_1
	v_cvt_f32_f16_e32 v236, v208
	v_cvt_f32_f16_sdwa v237, v208 dst_sel:DWORD dst_unused:UNUSED_PAD src0_sel:WORD_1
	v_cvt_f32_f16_e32 v238, v209
	v_cvt_f32_f16_sdwa v239, v209 dst_sel:DWORD dst_unused:UNUSED_PAD src0_sel:WORD_1
	v_cvt_f32_f16_e32 v240, v210
	v_cvt_f32_f16_sdwa v241, v210 dst_sel:DWORD dst_unused:UNUSED_PAD src0_sel:WORD_1
	v_cvt_f32_f16_e32 v242, v211
	v_cvt_f32_f16_sdwa v243, v211 dst_sel:DWORD dst_unused:UNUSED_PAD src0_sel:WORD_1
	v_pk_fma_f32 v[12:13], v[12:13], v[236:237], v[228:229]
	v_pk_fma_f32 v[14:15], v[14:15], v[238:239], v[230:231]
	v_pk_fma_f32 v[8:9], v[8:9], v[240:241], v[232:233]
	v_pk_fma_f32 v[10:11], v[10:11], v[242:243], v[234:235]
	v_cvt_pk_f16_f32 v204, v12, v13
	v_cvt_pk_f16_f32 v205, v14, v15
	v_cvt_pk_f16_f32 v206, v8, v9
	v_cvt_pk_f16_f32 v207, v10, v11
	global_store_dwordx4 v227, v[204:207], s[22:23] sc1
	s_nop 1
	s_waitcnt vmcnt(7)
	v_cvt_f32_f16_e32 v228, v212
	v_cvt_f32_f16_sdwa v229, v212 dst_sel:DWORD dst_unused:UNUSED_PAD src0_sel:WORD_1
	v_cvt_f32_f16_e32 v230, v213
	v_cvt_f32_f16_sdwa v231, v213 dst_sel:DWORD dst_unused:UNUSED_PAD src0_sel:WORD_1
	v_cvt_f32_f16_e32 v232, v214
	v_cvt_f32_f16_sdwa v233, v214 dst_sel:DWORD dst_unused:UNUSED_PAD src0_sel:WORD_1
	v_cvt_f32_f16_e32 v234, v215
	v_cvt_f32_f16_sdwa v235, v215 dst_sel:DWORD dst_unused:UNUSED_PAD src0_sel:WORD_1
	v_cvt_f32_f16_e32 v236, v216
	v_cvt_f32_f16_sdwa v237, v216 dst_sel:DWORD dst_unused:UNUSED_PAD src0_sel:WORD_1
	v_cvt_f32_f16_e32 v238, v217
	v_cvt_f32_f16_sdwa v239, v217 dst_sel:DWORD dst_unused:UNUSED_PAD src0_sel:WORD_1
	v_cvt_f32_f16_e32 v240, v218
	v_cvt_f32_f16_sdwa v241, v218 dst_sel:DWORD dst_unused:UNUSED_PAD src0_sel:WORD_1
	v_cvt_f32_f16_e32 v242, v219
	v_cvt_f32_f16_sdwa v243, v219 dst_sel:DWORD dst_unused:UNUSED_PAD src0_sel:WORD_1
	v_pk_fma_f32 v[4:5], v[4:5], v[236:237], v[228:229]
	v_pk_fma_f32 v[6:7], v[6:7], v[238:239], v[230:231]
	v_pk_fma_f32 v[0:1], v[0:1], v[240:241], v[232:233]
	v_pk_fma_f32 v[2:3], v[2:3], v[242:243], v[234:235]
	v_cvt_pk_f16_f32 v212, v4, v5
	v_cvt_pk_f16_f32 v213, v6, v7
	v_cvt_pk_f16_f32 v214, v0, v1
	v_cvt_pk_f16_f32 v215, v2, v3
	global_store_dwordx4 v227, v[212:215], s[22:23] offset:256 sc1
	s_nop 1
	s_waitcnt vmcnt(0)
	s_barrier
	v_mbcnt_lo_u32_b32 v0, -1, 0
	v_mbcnt_hi_u32_b32 v0, -1, v0
	s_nop 0
	v_or_b32_e32 v0, s97, v0
	v_cmp_eq_u32_e32 vcc, 0, v0
	s_and_saveexec_b64 s[10:11], vcc
	s_cbranch_execz .LBB0_596
	s_mov_b64 s[14:15], exec
	v_mbcnt_lo_u32_b32 v0, s14, 0
	v_mbcnt_hi_u32_b32 v0, s15, v0
	v_cmp_eq_u32_e32 vcc, 0, v0
	s_and_saveexec_b64 s[12:13], vcc
	s_cbranch_execz .LBB0_648
	s_lshl_b32 s0, s0, 6
	s_lshl_b64 s[16:17], s[0:1], 2
	s_add_u32 s16, s56, s16
	s_addc_u32 s17, s57, s17
	s_bcnt1_i32_b64 s0, s[14:15]
	v_mov_b32_e32 v0, s0
	global_atomic_add v129, v0, s[16:17]

.Lsh_k3:
	v_mov_b32_e32 v156, v136
	v_add_u32_e32 v157, 0x8000, v136
	v_add_u32_e32 v158, 0x10000, v136
	v_add_u32_e32 v159, 0x18000, v136
	v_add_u32_e32 v160, 0x40000, v136
	v_add_u32_e32 v161, 0x48000, v136
	v_add_u32_e32 v162, 0x50000, v136
	v_add_u32_e32 v163, 0x58000, v136
	global_load_dwordx4 v[164:167], v156, s[44:45] nt
	global_load_dwordx4 v[168:171], v156, s[44:45] offset:256 nt
	global_load_dwordx4 v[172:175], v157, s[44:45] nt
	global_load_dwordx4 v[176:179], v157, s[44:45] offset:256 nt
	global_load_dwordx4 v[180:183], v158, s[44:45] nt
	global_load_dwordx4 v[184:187], v158, s[44:45] offset:256 nt
	global_load_dwordx4 v[188:191], v159, s[44:45] nt
	global_load_dwordx4 v[192:195], v159, s[44:45] offset:256 nt
	s_waitcnt vmcnt(7)
	v_cvt_f32_f16_e32 v196, v164
	v_cvt_f32_f16_sdwa v197, v164 dst_sel:DWORD dst_unused:UNUSED_PAD src0_sel:WORD_1
	v_cvt_f32_f16_e32 v198, v165
	v_cvt_f32_f16_sdwa v199, v165 dst_sel:DWORD dst_unused:UNUSED_PAD src0_sel:WORD_1
	v_cvt_f32_f16_e32 v200, v166
	v_cvt_f32_f16_sdwa v201, v166 dst_sel:DWORD dst_unused:UNUSED_PAD src0_sel:WORD_1
	v_cvt_f32_f16_e32 v202, v167
	v_cvt_f32_f16_sdwa v203, v167 dst_sel:DWORD dst_unused:UNUSED_PAD src0_sel:WORD_1
	v_pk_mul_f32 v[124:125], v[124:125], v[196:197]
	v_pk_mul_f32 v[126:127], v[126:127], v[198:199]
	v_pk_mul_f32 v[120:121], v[120:121], v[200:201]
	v_pk_mul_f32 v[122:123], v[122:123], v[202:203]
	v_cvt_pk_f16_f32 v164, v124, v125
	v_cvt_pk_f16_f32 v165, v126, v127
	v_cvt_pk_f16_f32 v166, v120, v121
	v_cvt_pk_f16_f32 v167, v122, v123
	global_store_dwordx4 v156, v[164:167], s[44:45]
	s_nop 1
	global_load_dwordx4 v[164:167], v160, s[44:45] nt
	s_waitcnt vmcnt(8)
	v_cvt_f32_f16_e32 v196, v168
	v_cvt_f32_f16_sdwa v197, v168 dst_sel:DWORD dst_unused:UNUSED_PAD src0_sel:WORD_1
	v_cvt_f32_f16_e32 v198, v169
	v_cvt_f32_f16_sdwa v199, v169 dst_sel:DWORD dst_unused:UNUSED_PAD src0_sel:WORD_1
	v_cvt_f32_f16_e32 v200, v170
	v_cvt_f32_f16_sdwa v201, v170 dst_sel:DWORD dst_unused:UNUSED_PAD src0_sel:WORD_1
	v_cvt_f32_f16_e32 v202, v171
	v_cvt_f32_f16_sdwa v203, v171 dst_sel:DWORD dst_unused:UNUSED_PAD src0_sel:WORD_1
	v_pk_mul_f32 v[116:117], v[116:117], v[196:197]
	v_pk_mul_f32 v[118:119], v[118:119], v[198:199]
	v_pk_mul_f32 v[112:113], v[112:113], v[200:201]
	v_pk_mul_f32 v[114:115], v[114:115], v[202:203]
	v_cvt_pk_f16_f32 v168, v116, v117
	v_cvt_pk_f16_f32 v169, v118, v119
	v_cvt_pk_f16_f32 v170, v112, v113
	v_cvt_pk_f16_f32 v171, v114, v115
	global_store_dwordx4 v156, v[168:171], s[44:45] offset:256
	s_nop 1
	global_load_dwordx4 v[168:171], v160, s[44:45] offset:256 nt
	s_waitcnt vmcnt(9)
	v_cvt_f32_f16_e32 v196, v172
	v_cvt_f32_f16_sdwa v197, v172 dst_sel:DWORD dst_unused:UNUSED_PAD src0_sel:WORD_1
	v_cvt_f32_f16_e32 v198, v173
	v_cvt_f32_f16_sdwa v199, v173 dst_sel:DWORD dst_unused:UNUSED_PAD src0_sel:WORD_1
	v_cvt_f32_f16_e32 v200, v174
	v_cvt_f32_f16_sdwa v201, v174 dst_sel:DWORD dst_unused:UNUSED_PAD src0_sel:WORD_1
	v_cvt_f32_f16_e32 v202, v175
	v_cvt_f32_f16_sdwa v203, v175 dst_sel:DWORD dst_unused:UNUSED_PAD src0_sel:WORD_1
	v_pk_mul_f32 v[108:109], v[108:109], v[196:197]
	v_pk_mul_f32 v[110:111], v[110:111], v[198:199]
	v_pk_mul_f32 v[104:105], v[104:105], v[200:201]
	v_pk_mul_f32 v[106:107], v[106:107], v[202:203]
	v_cvt_pk_f16_f32 v172, v108, v109
	v_cvt_pk_f16_f32 v173, v110, v111
	v_cvt_pk_f16_f32 v174, v104, v105
	v_cvt_pk_f16_f32 v175, v106, v107
	global_store_dwordx4 v157, v[172:175], s[44:45]
	s_nop 1
	global_load_dwordx4 v[172:175], v161, s[44:45] nt
	s_waitcnt vmcnt(10)
	v_cvt_f32_f16_e32 v196, v176
	v_cvt_f32_f16_sdwa v197, v176 dst_sel:DWORD dst_unused:UNUSED_PAD src0_sel:WORD_1
	v_cvt_f32_f16_e32 v198, v177
	v_cvt_f32_f16_sdwa v199, v177 dst_sel:DWORD dst_unused:UNUSED_PAD src0_sel:WORD_1
	v_cvt_f32_f16_e32 v200, v178
	v_cvt_f32_f16_sdwa v201, v178 dst_sel:DWORD dst_unused:UNUSED_PAD src0_sel:WORD_1
	v_cvt_f32_f16_e32 v202, v179
	v_cvt_f32_f16_sdwa v203, v179 dst_sel:DWORD dst_unused:UNUSED_PAD src0_sel:WORD_1
	v_pk_mul_f32 v[100:101], v[100:101], v[196:197]
	v_pk_mul_f32 v[102:103], v[102:103], v[198:199]
	v_pk_mul_f32 v[96:97], v[96:97], v[200:201]
	v_pk_mul_f32 v[98:99], v[98:99], v[202:203]
	v_cvt_pk_f16_f32 v176, v100, v101
	v_cvt_pk_f16_f32 v177, v102, v103
	v_cvt_pk_f16_f32 v178, v96, v97
	v_cvt_pk_f16_f32 v179, v98, v99
	global_store_dwordx4 v157, v[176:179], s[44:45] offset:256
	s_nop 1
	global_load_dwordx4 v[176:179], v161, s[44:45] offset:256 nt
	s_waitcnt vmcnt(11)
	v_cvt_f32_f16_e32 v196, v180
	v_cvt_f32_f16_sdwa v197, v180 dst_sel:DWORD dst_unused:UNUSED_PAD src0_sel:WORD_1
	v_cvt_f32_f16_e32 v198, v181
	v_cvt_f32_f16_sdwa v199, v181 dst_sel:DWORD dst_unused:UNUSED_PAD src0_sel:WORD_1
	v_cvt_f32_f16_e32 v200, v182
	v_cvt_f32_f16_sdwa v201, v182 dst_sel:DWORD dst_unused:UNUSED_PAD src0_sel:WORD_1
	v_cvt_f32_f16_e32 v202, v183
	v_cvt_f32_f16_sdwa v203, v183 dst_sel:DWORD dst_unused:UNUSED_PAD src0_sel:WORD_1
	v_pk_mul_f32 v[92:93], v[92:93], v[196:197]
	v_pk_mul_f32 v[94:95], v[94:95], v[198:199]
	v_pk_mul_f32 v[88:89], v[88:89], v[200:201]
	v_pk_mul_f32 v[90:91], v[90:91], v[202:203]
	v_cvt_pk_f16_f32 v180, v92, v93
	v_cvt_pk_f16_f32 v181, v94, v95
	v_cvt_pk_f16_f32 v182, v88, v89
	v_cvt_pk_f16_f32 v183, v90, v91
	global_store_dwordx4 v158, v[180:183], s[44:45]
	s_nop 1
	global_load_dwordx4 v[180:183], v162, s[44:45] nt
	s_waitcnt vmcnt(12)
	v_cvt_f32_f16_e32 v196, v184
	v_cvt_f32_f16_sdwa v197, v184 dst_sel:DWORD dst_unused:UNUSED_PAD src0_sel:WORD_1
	v_cvt_f32_f16_e32 v198, v185
	v_cvt_f32_f16_sdwa v199, v185 dst_sel:DWORD dst_unused:UNUSED_PAD src0_sel:WORD_1
	v_cvt_f32_f16_e32 v200, v186
	v_cvt_f32_f16_sdwa v201, v186 dst_sel:DWORD dst_unused:UNUSED_PAD src0_sel:WORD_1
	v_cvt_f32_f16_e32 v202, v187
	v_cvt_f32_f16_sdwa v203, v187 dst_sel:DWORD dst_unused:UNUSED_PAD src0_sel:WORD_1
	v_pk_mul_f32 v[84:85], v[84:85], v[196:197]
	v_pk_mul_f32 v[86:87], v[86:87], v[198:199]
	v_pk_mul_f32 v[80:81], v[80:81], v[200:201]
	v_pk_mul_f32 v[82:83], v[82:83], v[202:203]
	v_cvt_pk_f16_f32 v184, v84, v85
	v_cvt_pk_f16_f32 v185, v86, v87
	v_cvt_pk_f16_f32 v186, v80, v81
	v_cvt_pk_f16_f32 v187, v82, v83
	global_store_dwordx4 v158, v[184:187], s[44:45] offset:256
	s_nop 1
	global_load_dwordx4 v[184:187], v162, s[44:45] offset:256 nt
	s_waitcnt vmcnt(13)
	v_cvt_f32_f16_e32 v196, v188
	v_cvt_f32_f16_sdwa v197, v188 dst_sel:DWORD dst_unused:UNUSED_PAD src0_sel:WORD_1
	v_cvt_f32_f16_e32 v198, v189
	v_cvt_f32_f16_sdwa v199, v189 dst_sel:DWORD dst_unused:UNUSED_PAD src0_sel:WORD_1
	v_cvt_f32_f16_e32 v200, v190
	v_cvt_f32_f16_sdwa v201, v190 dst_sel:DWORD dst_unused:UNUSED_PAD src0_sel:WORD_1
	v_cvt_f32_f16_e32 v202, v191
	v_cvt_f32_f16_sdwa v203, v191 dst_sel:DWORD dst_unused:UNUSED_PAD src0_sel:WORD_1
	v_pk_mul_f32 v[76:77], v[76:77], v[196:197]
	v_pk_mul_f32 v[78:79], v[78:79], v[198:199]
	v_pk_mul_f32 v[72:73], v[72:73], v[200:201]
	v_pk_mul_f32 v[74:75], v[74:75], v[202:203]
	v_cvt_pk_f16_f32 v188, v76, v77
	v_cvt_pk_f16_f32 v189, v78, v79
	v_cvt_pk_f16_f32 v190, v72, v73
	v_cvt_pk_f16_f32 v191, v74, v75
	global_store_dwordx4 v159, v[188:191], s[44:45]
	s_nop 1
	global_load_dwordx4 v[188:191], v163, s[44:45] nt
	s_waitcnt vmcnt(14)
	v_cvt_f32_f16_e32 v196, v192
	v_cvt_f32_f16_sdwa v197, v192 dst_sel:DWORD dst_unused:UNUSED_PAD src0_sel:WORD_1
	v_cvt_f32_f16_e32 v198, v193
	v_cvt_f32_f16_sdwa v199, v193 dst_sel:DWORD dst_unused:UNUSED_PAD src0_sel:WORD_1
	v_cvt_f32_f16_e32 v200, v194
	v_cvt_f32_f16_sdwa v201, v194 dst_sel:DWORD dst_unused:UNUSED_PAD src0_sel:WORD_1
	v_cvt_f32_f16_e32 v202, v195
	v_cvt_f32_f16_sdwa v203, v195 dst_sel:DWORD dst_unused:UNUSED_PAD src0_sel:WORD_1
	v_pk_mul_f32 v[68:69], v[68:69], v[196:197]
	v_pk_mul_f32 v[70:71], v[70:71], v[198:199]
	v_pk_mul_f32 v[64:65], v[64:65], v[200:201]
	v_pk_mul_f32 v[66:67], v[66:67], v[202:203]
	v_cvt_pk_f16_f32 v192, v68, v69
	v_cvt_pk_f16_f32 v193, v70, v71
	v_cvt_pk_f16_f32 v194, v64, v65
	v_cvt_pk_f16_f32 v195, v66, v67
	global_store_dwordx4 v159, v[192:195], s[44:45] offset:256
	s_nop 1
	global_load_dwordx4 v[192:195], v163, s[44:45] offset:256 nt
	s_waitcnt vmcnt(14)
	v_cvt_f32_f16_e32 v196, v164
	v_cvt_f32_f16_sdwa v197, v164 dst_sel:DWORD dst_unused:UNUSED_PAD src0_sel:WORD_1
	v_cvt_f32_f16_e32 v198, v165
	v_cvt_f32_f16_sdwa v199, v165 dst_sel:DWORD dst_unused:UNUSED_PAD src0_sel:WORD_1
	v_cvt_f32_f16_e32 v200, v166
	v_cvt_f32_f16_sdwa v201, v166 dst_sel:DWORD dst_unused:UNUSED_PAD src0_sel:WORD_1
	v_cvt_f32_f16_e32 v202, v167
	v_cvt_f32_f16_sdwa v203, v167 dst_sel:DWORD dst_unused:UNUSED_PAD src0_sel:WORD_1
	v_pk_mul_f32 v[60:61], v[60:61], v[196:197]
	v_pk_mul_f32 v[62:63], v[62:63], v[198:199]
	v_pk_mul_f32 v[56:57], v[56:57], v[200:201]
	v_pk_mul_f32 v[58:59], v[58:59], v[202:203]
	v_cvt_pk_f16_f32 v164, v60, v61
	v_cvt_pk_f16_f32 v165, v62, v63
	v_cvt_pk_f16_f32 v166, v56, v57
	v_cvt_pk_f16_f32 v167, v58, v59
	global_store_dwordx4 v160, v[164:167], s[44:45]
	s_nop 1
	s_waitcnt vmcnt(13)
	v_cvt_f32_f16_e32 v196, v168
	v_cvt_f32_f16_sdwa v197, v168 dst_sel:DWORD dst_unused:UNUSED_PAD src0_sel:WORD_1
	v_cvt_f32_f16_e32 v198, v169
	v_cvt_f32_f16_sdwa v199, v169 dst_sel:DWORD dst_unused:UNUSED_PAD src0_sel:WORD_1
	v_cvt_f32_f16_e32 v200, v170
	v_cvt_f32_f16_sdwa v201, v170 dst_sel:DWORD dst_unused:UNUSED_PAD src0_sel:WORD_1
	v_cvt_f32_f16_e32 v202, v171
	v_cvt_f32_f16_sdwa v203, v171 dst_sel:DWORD dst_unused:UNUSED_PAD src0_sel:WORD_1
	v_pk_mul_f32 v[52:53], v[52:53], v[196:197]
	v_pk_mul_f32 v[54:55], v[54:55], v[198:199]
	v_pk_mul_f32 v[48:49], v[48:49], v[200:201]
	v_pk_mul_f32 v[50:51], v[50:51], v[202:203]
	v_cvt_pk_f16_f32 v168, v52, v53
	v_cvt_pk_f16_f32 v169, v54, v55
	v_cvt_pk_f16_f32 v170, v48, v49
	v_cvt_pk_f16_f32 v171, v50, v51
	global_store_dwordx4 v160, v[168:171], s[44:45] offset:256
	s_nop 1
	s_waitcnt vmcnt(12)
	v_cvt_f32_f16_e32 v196, v172
	v_cvt_f32_f16_sdwa v197, v172 dst_sel:DWORD dst_unused:UNUSED_PAD src0_sel:WORD_1
	v_cvt_f32_f16_e32 v198, v173
	v_cvt_f32_f16_sdwa v199, v173 dst_sel:DWORD dst_unused:UNUSED_PAD src0_sel:WORD_1
	v_cvt_f32_f16_e32 v200, v174
	v_cvt_f32_f16_sdwa v201, v174 dst_sel:DWORD dst_unused:UNUSED_PAD src0_sel:WORD_1
	v_cvt_f32_f16_e32 v202, v175
	v_cvt_f32_f16_sdwa v203, v175 dst_sel:DWORD dst_unused:UNUSED_PAD src0_sel:WORD_1
	v_pk_mul_f32 v[44:45], v[44:45], v[196:197]
	v_pk_mul_f32 v[46:47], v[46:47], v[198:199]
	v_pk_mul_f32 v[40:41], v[40:41], v[200:201]
	v_pk_mul_f32 v[42:43], v[42:43], v[202:203]
	v_cvt_pk_f16_f32 v172, v44, v45
	v_cvt_pk_f16_f32 v173, v46, v47
	v_cvt_pk_f16_f32 v174, v40, v41
	v_cvt_pk_f16_f32 v175, v42, v43
	global_store_dwordx4 v161, v[172:175], s[44:45]
	s_nop 1
	s_waitcnt vmcnt(11)
	v_cvt_f32_f16_e32 v196, v176
	v_cvt_f32_f16_sdwa v197, v176 dst_sel:DWORD dst_unused:UNUSED_PAD src0_sel:WORD_1
	v_cvt_f32_f16_e32 v198, v177
	v_cvt_f32_f16_sdwa v199, v177 dst_sel:DWORD dst_unused:UNUSED_PAD src0_sel:WORD_1
	v_cvt_f32_f16_e32 v200, v178
	v_cvt_f32_f16_sdwa v201, v178 dst_sel:DWORD dst_unused:UNUSED_PAD src0_sel:WORD_1
	v_cvt_f32_f16_e32 v202, v179
	v_cvt_f32_f16_sdwa v203, v179 dst_sel:DWORD dst_unused:UNUSED_PAD src0_sel:WORD_1
	v_pk_mul_f32 v[36:37], v[36:37], v[196:197]
	v_pk_mul_f32 v[38:39], v[38:39], v[198:199]
	v_pk_mul_f32 v[32:33], v[32:33], v[200:201]
	v_pk_mul_f32 v[34:35], v[34:35], v[202:203]
	v_cvt_pk_f16_f32 v176, v36, v37
	v_cvt_pk_f16_f32 v177, v38, v39
	v_cvt_pk_f16_f32 v178, v32, v33
	v_cvt_pk_f16_f32 v179, v34, v35
	global_store_dwordx4 v161, v[176:179], s[44:45] offset:256
	s_nop 1
	s_waitcnt vmcnt(10)
	v_cvt_f32_f16_e32 v196, v180
	v_cvt_f32_f16_sdwa v197, v180 dst_sel:DWORD dst_unused:UNUSED_PAD src0_sel:WORD_1
	v_cvt_f32_f16_e32 v198, v181
	v_cvt_f32_f16_sdwa v199, v181 dst_sel:DWORD dst_unused:UNUSED_PAD src0_sel:WORD_1
	v_cvt_f32_f16_e32 v200, v182
	v_cvt_f32_f16_sdwa v201, v182 dst_sel:DWORD dst_unused:UNUSED_PAD src0_sel:WORD_1
	v_cvt_f32_f16_e32 v202, v183
	v_cvt_f32_f16_sdwa v203, v183 dst_sel:DWORD dst_unused:UNUSED_PAD src0_sel:WORD_1
	v_pk_mul_f32 v[28:29], v[28:29], v[196:197]
	v_pk_mul_f32 v[30:31], v[30:31], v[198:199]
	v_pk_mul_f32 v[24:25], v[24:25], v[200:201]
	v_pk_mul_f32 v[26:27], v[26:27], v[202:203]
	v_cvt_pk_f16_f32 v180, v28, v29
	v_cvt_pk_f16_f32 v181, v30, v31
	v_cvt_pk_f16_f32 v182, v24, v25
	v_cvt_pk_f16_f32 v183, v26, v27
	global_store_dwordx4 v162, v[180:183], s[44:45]
	s_nop 1
	s_waitcnt vmcnt(9)
	v_cvt_f32_f16_e32 v196, v184
	v_cvt_f32_f16_sdwa v197, v184 dst_sel:DWORD dst_unused:UNUSED_PAD src0_sel:WORD_1
	v_cvt_f32_f16_e32 v198, v185
	v_cvt_f32_f16_sdwa v199, v185 dst_sel:DWORD dst_unused:UNUSED_PAD src0_sel:WORD_1
	v_cvt_f32_f16_e32 v200, v186
	v_cvt_f32_f16_sdwa v201, v186 dst_sel:DWORD dst_unused:UNUSED_PAD src0_sel:WORD_1
	v_cvt_f32_f16_e32 v202, v187
	v_cvt_f32_f16_sdwa v203, v187 dst_sel:DWORD dst_unused:UNUSED_PAD src0_sel:WORD_1
	v_pk_mul_f32 v[20:21], v[20:21], v[196:197]
	v_pk_mul_f32 v[22:23], v[22:23], v[198:199]
	v_pk_mul_f32 v[16:17], v[16:17], v[200:201]
	v_pk_mul_f32 v[18:19], v[18:19], v[202:203]
	v_cvt_pk_f16_f32 v184, v20, v21
	v_cvt_pk_f16_f32 v185, v22, v23
	v_cvt_pk_f16_f32 v186, v16, v17
	v_cvt_pk_f16_f32 v187, v18, v19
	global_store_dwordx4 v162, v[184:187], s[44:45] offset:256
	s_nop 1
	s_waitcnt vmcnt(8)
	v_cvt_f32_f16_e32 v196, v188
	v_cvt_f32_f16_sdwa v197, v188 dst_sel:DWORD dst_unused:UNUSED_PAD src0_sel:WORD_1
	v_cvt_f32_f16_e32 v198, v189
	v_cvt_f32_f16_sdwa v199, v189 dst_sel:DWORD dst_unused:UNUSED_PAD src0_sel:WORD_1
	v_cvt_f32_f16_e32 v200, v190
	v_cvt_f32_f16_sdwa v201, v190 dst_sel:DWORD dst_unused:UNUSED_PAD src0_sel:WORD_1
	v_cvt_f32_f16_e32 v202, v191
	v_cvt_f32_f16_sdwa v203, v191 dst_sel:DWORD dst_unused:UNUSED_PAD src0_sel:WORD_1
	v_pk_mul_f32 v[12:13], v[12:13], v[196:197]
	v_pk_mul_f32 v[14:15], v[14:15], v[198:199]
	v_pk_mul_f32 v[8:9], v[8:9], v[200:201]
	v_pk_mul_f32 v[10:11], v[10:11], v[202:203]
	v_cvt_pk_f16_f32 v188, v12, v13
	v_cvt_pk_f16_f32 v189, v14, v15
	v_cvt_pk_f16_f32 v190, v8, v9
	v_cvt_pk_f16_f32 v191, v10, v11
	global_store_dwordx4 v163, v[188:191], s[44:45]
	s_nop 1
	s_waitcnt vmcnt(7)
	v_cvt_f32_f16_e32 v196, v192
	v_cvt_f32_f16_sdwa v197, v192 dst_sel:DWORD dst_unused:UNUSED_PAD src0_sel:WORD_1
	v_cvt_f32_f16_e32 v198, v193
	v_cvt_f32_f16_sdwa v199, v193 dst_sel:DWORD dst_unused:UNUSED_PAD src0_sel:WORD_1
	v_cvt_f32_f16_e32 v200, v194
	v_cvt_f32_f16_sdwa v201, v194 dst_sel:DWORD dst_unused:UNUSED_PAD src0_sel:WORD_1
	v_cvt_f32_f16_e32 v202, v195
	v_cvt_f32_f16_sdwa v203, v195 dst_sel:DWORD dst_unused:UNUSED_PAD src0_sel:WORD_1
	v_pk_mul_f32 v[4:5], v[4:5], v[196:197]
	v_pk_mul_f32 v[6:7], v[6:7], v[198:199]
	v_pk_mul_f32 v[0:1], v[0:1], v[200:201]
	v_pk_mul_f32 v[2:3], v[2:3], v[202:203]
	v_cvt_pk_f16_f32 v192, v4, v5
	v_cvt_pk_f16_f32 v193, v6, v7
	v_cvt_pk_f16_f32 v194, v0, v1
	v_cvt_pk_f16_f32 v195, v2, v3
	global_store_dwordx4 v163, v[192:195], s[44:45] offset:256
	s_nop 1
	s_branch .LBB0_1145

.LBB0_1235:
	v_readlane_b32 s12, v255, 0
	v_or_b32_e32 v130, s54, v143
	v_lshl_or_b32 v131, v142, 11, s55
	s_lshl_b32 s10, s20, 9
	v_readlane_b32 s13, v255, 1
	v_readlane_b32 s14, v255, 2
	v_readlane_b32 s15, v255, 3
	v_readlane_b32 s16, v255, 4
	v_readlane_b32 s17, v255, 5
	v_or_b32_e32 v128, v131, v130
	s_or_b32 s10, s21, s10
	v_readlane_b32 s18, v255, 6
	v_readlane_b32 s19, v255, 7
	s_mov_b64 s[12:13], s[16:17]
	v_add_u32_e32 v128, s10, v128
	s_mov_b64 s[14:15], s[18:19]
	v_mov_b32_e32 v220, v128
	v_add_u32_e32 v221, 0x8000, v128
	v_add_u32_e32 v222, 0x10000, v128
	v_add_u32_e32 v223, 0x18000, v128
	v_add_u32_e32 v224, 0x40000, v128
	v_add_u32_e32 v225, 0x48000, v128
	v_add_u32_e32 v226, 0x50000, v128
	v_add_u32_e32 v227, 0x58000, v128
	global_load_dwordx4 v[156:159], v220, s[24:25] nt
	global_load_dwordx4 v[160:163], v220, s[14:15] nt
	global_load_dwordx4 v[164:167], v220, s[24:25] offset:256 nt
	global_load_dwordx4 v[168:171], v220, s[14:15] offset:256 nt
	global_load_dwordx4 v[172:175], v221, s[24:25] nt
	global_load_dwordx4 v[176:179], v221, s[14:15] nt
	global_load_dwordx4 v[180:183], v221, s[24:25] offset:256 nt
	global_load_dwordx4 v[184:187], v221, s[14:15] offset:256 nt
	global_load_dwordx4 v[188:191], v222, s[24:25] nt
	global_load_dwordx4 v[192:195], v222, s[14:15] nt
	global_load_dwordx4 v[196:199], v222, s[24:25] offset:256 nt
	global_load_dwordx4 v[200:203], v222, s[14:15] offset:256 nt
	global_load_dwordx4 v[204:207], v223, s[24:25] nt
	global_load_dwordx4 v[208:211], v223, s[14:15] nt
	global_load_dwordx4 v[212:215], v223, s[24:25] offset:256 nt
	global_load_dwordx4 v[216:219], v223, s[14:15] offset:256 nt
	s_waitcnt vmcnt(14)
	v_cvt_f32_f16_e32 v228, v156
	v_cvt_f32_f16_sdwa v229, v156 dst_sel:DWORD dst_unused:UNUSED_PAD src0_sel:WORD_1
	v_cvt_f32_f16_e32 v230, v157
	v_cvt_f32_f16_sdwa v231, v157 dst_sel:DWORD dst_unused:UNUSED_PAD src0_sel:WORD_1
	v_cvt_f32_f16_e32 v232, v158
	v_cvt_f32_f16_sdwa v233, v158 dst_sel:DWORD dst_unused:UNUSED_PAD src0_sel:WORD_1
	v_cvt_f32_f16_e32 v234, v159
	v_cvt_f32_f16_sdwa v235, v159 dst_sel:DWORD dst_unused:UNUSED_PAD src0_sel:WORD_1
	v_cvt_f32_f16_e32 v236, v160
	v_cvt_f32_f16_sdwa v237, v160 dst_sel:DWORD dst_unused:UNUSED_PAD src0_sel:WORD_1
	v_cvt_f32_f16_e32 v238, v161
	v_cvt_f32_f16_sdwa v239, v161 dst_sel:DWORD dst_unused:UNUSED_PAD src0_sel:WORD_1
	v_cvt_f32_f16_e32 v240, v162
	v_cvt_f32_f16_sdwa v241, v162 dst_sel:DWORD dst_unused:UNUSED_PAD src0_sel:WORD_1
	v_cvt_f32_f16_e32 v242, v163
	v_cvt_f32_f16_sdwa v243, v163 dst_sel:DWORD dst_unused:UNUSED_PAD src0_sel:WORD_1
	v_pk_fma_f32 v[124:125], v[124:125], v[236:237], v[228:229]
	v_pk_fma_f32 v[126:127], v[126:127], v[238:239], v[230:231]
	v_pk_fma_f32 v[120:121], v[120:121], v[240:241], v[232:233]
	v_pk_fma_f32 v[122:123], v[122:123], v[242:243], v[234:235]
	v_cvt_pk_f16_f32 v156, v124, v125
	v_cvt_pk_f16_f32 v157, v126, v127
	v_cvt_pk_f16_f32 v158, v120, v121
	v_cvt_pk_f16_f32 v159, v122, v123
	global_store_dwordx4 v220, v[156:159], s[22:23] sc1
	s_nop 1
	global_load_dwordx4 v[156:159], v224, s[24:25] nt
	global_load_dwordx4 v[160:163], v224, s[14:15] nt
	s_waitcnt vmcnt(15)
	v_cvt_f32_f16_e32 v228, v164
	v_cvt_f32_f16_sdwa v229, v164 dst_sel:DWORD dst_unused:UNUSED_PAD src0_sel:WORD_1
	v_cvt_f32_f16_e32 v230, v165
	v_cvt_f32_f16_sdwa v231, v165 dst_sel:DWORD dst_unused:UNUSED_PAD src0_sel:WORD_1
	v_cvt_f32_f16_e32 v232, v166
	v_cvt_f32_f16_sdwa v233, v166 dst_sel:DWORD dst_unused:UNUSED_PAD src0_sel:WORD_1
	v_cvt_f32_f16_e32 v234, v167
	v_cvt_f32_f16_sdwa v235, v167 dst_sel:DWORD dst_unused:UNUSED_PAD src0_sel:WORD_1
	v_cvt_f32_f16_e32 v236, v168
	v_cvt_f32_f16_sdwa v237, v168 dst_sel:DWORD dst_unused:UNUSED_PAD src0_sel:WORD_1
	v_cvt_f32_f16_e32 v238, v169
	v_cvt_f32_f16_sdwa v239, v169 dst_sel:DWORD dst_unused:UNUSED_PAD src0_sel:WORD_1
	v_cvt_f32_f16_e32 v240, v170
	v_cvt_f32_f16_sdwa v241, v170 dst_sel:DWORD dst_unused:UNUSED_PAD src0_sel:WORD_1
	v_cvt_f32_f16_e32 v242, v171
	v_cvt_f32_f16_sdwa v243, v171 dst_sel:DWORD dst_unused:UNUSED_PAD src0_sel:WORD_1
	v_pk_fma_f32 v[116:117], v[116:117], v[236:237], v[228:229]
	v_pk_fma_f32 v[118:119], v[118:119], v[238:239], v[230:231]
	v_pk_fma_f32 v[112:113], v[112:113], v[240:241], v[232:233]
	v_pk_fma_f32 v[114:115], v[114:115], v[242:243], v[234:235]
	v_cvt_pk_f16_f32 v164, v116, v117
	v_cvt_pk_f16_f32 v165, v118, v119
	v_cvt_pk_f16_f32 v166, v112, v113
	v_cvt_pk_f16_f32 v167, v114, v115
	global_store_dwordx4 v220, v[164:167], s[22:23] offset:256 sc1
	s_nop 1
	global_load_dwordx4 v[164:167], v224, s[24:25] offset:256 nt
	global_load_dwordx4 v[168:171], v224, s[14:15] offset:256 nt
	s_waitcnt vmcnt(16)
	v_cvt_f32_f16_e32 v228, v172
	v_cvt_f32_f16_sdwa v229, v172 dst_sel:DWORD dst_unused:UNUSED_PAD src0_sel:WORD_1
	v_cvt_f32_f16_e32 v230, v173
	v_cvt_f32_f16_sdwa v231, v173 dst_sel:DWORD dst_unused:UNUSED_PAD src0_sel:WORD_1
	v_cvt_f32_f16_e32 v232, v174
	v_cvt_f32_f16_sdwa v233, v174 dst_sel:DWORD dst_unused:UNUSED_PAD src0_sel:WORD_1
	v_cvt_f32_f16_e32 v234, v175
	v_cvt_f32_f16_sdwa v235, v175 dst_sel:DWORD dst_unused:UNUSED_PAD src0_sel:WORD_1
	v_cvt_f32_f16_e32 v236, v176
	v_cvt_f32_f16_sdwa v237, v176 dst_sel:DWORD dst_unused:UNUSED_PAD src0_sel:WORD_1
	v_cvt_f32_f16_e32 v238, v177
	v_cvt_f32_f16_sdwa v239, v177 dst_sel:DWORD dst_unused:UNUSED_PAD src0_sel:WORD_1
	v_cvt_f32_f16_e32 v240, v178
	v_cvt_f32_f16_sdwa v241, v178 dst_sel:DWORD dst_unused:UNUSED_PAD src0_sel:WORD_1
	v_cvt_f32_f16_e32 v242, v179
	v_cvt_f32_f16_sdwa v243, v179 dst_sel:DWORD dst_unused:UNUSED_PAD src0_sel:WORD_1
	v_pk_fma_f32 v[108:109], v[108:109], v[236:237], v[228:229]
	v_pk_fma_f32 v[110:111], v[110:111], v[238:239], v[230:231]
	v_pk_fma_f32 v[104:105], v[104:105], v[240:241], v[232:233]
	v_pk_fma_f32 v[106:107], v[106:107], v[242:243], v[234:235]
	v_cvt_pk_f16_f32 v172, v108, v109
	v_cvt_pk_f16_f32 v173, v110, v111
	v_cvt_pk_f16_f32 v174, v104, v105
	v_cvt_pk_f16_f32 v175, v106, v107
	global_store_dwordx4 v221, v[172:175], s[22:23] sc1
	s_nop 1
	global_load_dwordx4 v[172:175], v225, s[24:25] nt
	global_load_dwordx4 v[176:179], v225, s[14:15] nt
	s_waitcnt vmcnt(17)
	v_cvt_f32_f16_e32 v228, v180
	v_cvt_f32_f16_sdwa v229, v180 dst_sel:DWORD dst_unused:UNUSED_PAD src0_sel:WORD_1
	v_cvt_f32_f16_e32 v230, v181
	v_cvt_f32_f16_sdwa v231, v181 dst_sel:DWORD dst_unused:UNUSED_PAD src0_sel:WORD_1
	v_cvt_f32_f16_e32 v232, v182
	v_cvt_f32_f16_sdwa v233, v182 dst_sel:DWORD dst_unused:UNUSED_PAD src0_sel:WORD_1
	v_cvt_f32_f16_e32 v234, v183
	v_cvt_f32_f16_sdwa v235, v183 dst_sel:DWORD dst_unused:UNUSED_PAD src0_sel:WORD_1
	v_cvt_f32_f16_e32 v236, v184
	v_cvt_f32_f16_sdwa v237, v184 dst_sel:DWORD dst_unused:UNUSED_PAD src0_sel:WORD_1
	v_cvt_f32_f16_e32 v238, v185
	v_cvt_f32_f16_sdwa v239, v185 dst_sel:DWORD dst_unused:UNUSED_PAD src0_sel:WORD_1
	v_cvt_f32_f16_e32 v240, v186
	v_cvt_f32_f16_sdwa v241, v186 dst_sel:DWORD dst_unused:UNUSED_PAD src0_sel:WORD_1
	v_cvt_f32_f16_e32 v242, v187
	v_cvt_f32_f16_sdwa v243, v187 dst_sel:DWORD dst_unused:UNUSED_PAD src0_sel:WORD_1
	v_pk_fma_f32 v[100:101], v[100:101], v[236:237], v[228:229]
	v_pk_fma_f32 v[102:103], v[102:103], v[238:239], v[230:231]
	v_pk_fma_f32 v[96:97], v[96:97], v[240:241], v[232:233]
	v_pk_fma_f32 v[98:99], v[98:99], v[242:243], v[234:235]
	v_cvt_pk_f16_f32 v180, v100, v101
	v_cvt_pk_f16_f32 v181, v102, v103
	v_cvt_pk_f16_f32 v182, v96, v97
	v_cvt_pk_f16_f32 v183, v98, v99
	global_store_dwordx4 v221, v[180:183], s[22:23] offset:256 sc1
	s_nop 1
	global_load_dwordx4 v[180:183], v225, s[24:25] offset:256 nt
	global_load_dwordx4 v[184:187], v225, s[14:15] offset:256 nt
	s_waitcnt vmcnt(18)
	v_cvt_f32_f16_e32 v228, v188
	v_cvt_f32_f16_sdwa v229, v188 dst_sel:DWORD dst_unused:UNUSED_PAD src0_sel:WORD_1
	v_cvt_f32_f16_e32 v230, v189
	v_cvt_f32_f16_sdwa v231, v189 dst_sel:DWORD dst_unused:UNUSED_PAD src0_sel:WORD_1
	v_cvt_f32_f16_e32 v232, v190
	v_cvt_f32_f16_sdwa v233, v190 dst_sel:DWORD dst_unused:UNUSED_PAD src0_sel:WORD_1
	v_cvt_f32_f16_e32 v234, v191
	v_cvt_f32_f16_sdwa v235, v191 dst_sel:DWORD dst_unused:UNUSED_PAD src0_sel:WORD_1
	v_cvt_f32_f16_e32 v236, v192
	v_cvt_f32_f16_sdwa v237, v192 dst_sel:DWORD dst_unused:UNUSED_PAD src0_sel:WORD_1
	v_cvt_f32_f16_e32 v238, v193
	v_cvt_f32_f16_sdwa v239, v193 dst_sel:DWORD dst_unused:UNUSED_PAD src0_sel:WORD_1
	v_cvt_f32_f16_e32 v240, v194
	v_cvt_f32_f16_sdwa v241, v194 dst_sel:DWORD dst_unused:UNUSED_PAD src0_sel:WORD_1
	v_cvt_f32_f16_e32 v242, v195
	v_cvt_f32_f16_sdwa v243, v195 dst_sel:DWORD dst_unused:UNUSED_PAD src0_sel:WORD_1
	v_pk_fma_f32 v[92:93], v[92:93], v[236:237], v[228:229]
	v_pk_fma_f32 v[94:95], v[94:95], v[238:239], v[230:231]
	v_pk_fma_f32 v[88:89], v[88:89], v[240:241], v[232:233]
	v_pk_fma_f32 v[90:91], v[90:91], v[242:243], v[234:235]
	v_cvt_pk_f16_f32 v188, v92, v93
	v_cvt_pk_f16_f32 v189, v94, v95
	v_cvt_pk_f16_f32 v190, v88, v89
	v_cvt_pk_f16_f32 v191, v90, v91
	global_store_dwordx4 v222, v[188:191], s[22:23] sc1
	s_nop 1
	global_load_dwordx4 v[188:191], v226, s[24:25] nt
	global_load_dwordx4 v[192:195], v226, s[14:15] nt
	s_waitcnt vmcnt(19)
	v_cvt_f32_f16_e32 v228, v196
	v_cvt_f32_f16_sdwa v229, v196 dst_sel:DWORD dst_unused:UNUSED_PAD src0_sel:WORD_1
	v_cvt_f32_f16_e32 v230, v197
	v_cvt_f32_f16_sdwa v231, v197 dst_sel:DWORD dst_unused:UNUSED_PAD src0_sel:WORD_1
	v_cvt_f32_f16_e32 v232, v198
	v_cvt_f32_f16_sdwa v233, v198 dst_sel:DWORD dst_unused:UNUSED_PAD src0_sel:WORD_1
	v_cvt_f32_f16_e32 v234, v199
	v_cvt_f32_f16_sdwa v235, v199 dst_sel:DWORD dst_unused:UNUSED_PAD src0_sel:WORD_1
	v_cvt_f32_f16_e32 v236, v200
	v_cvt_f32_f16_sdwa v237, v200 dst_sel:DWORD dst_unused:UNUSED_PAD src0_sel:WORD_1
	v_cvt_f32_f16_e32 v238, v201
	v_cvt_f32_f16_sdwa v239, v201 dst_sel:DWORD dst_unused:UNUSED_PAD src0_sel:WORD_1
	v_cvt_f32_f16_e32 v240, v202
	v_cvt_f32_f16_sdwa v241, v202 dst_sel:DWORD dst_unused:UNUSED_PAD src0_sel:WORD_1
	v_cvt_f32_f16_e32 v242, v203
	v_cvt_f32_f16_sdwa v243, v203 dst_sel:DWORD dst_unused:UNUSED_PAD src0_sel:WORD_1
	v_pk_fma_f32 v[84:85], v[84:85], v[236:237], v[228:229]
	v_pk_fma_f32 v[86:87], v[86:87], v[238:239], v[230:231]
	v_pk_fma_f32 v[80:81], v[80:81], v[240:241], v[232:233]
	v_pk_fma_f32 v[82:83], v[82:83], v[242:243], v[234:235]
	v_cvt_pk_f16_f32 v196, v84, v85
	v_cvt_pk_f16_f32 v197, v86, v87
	v_cvt_pk_f16_f32 v198, v80, v81
	v_cvt_pk_f16_f32 v199, v82, v83
	global_store_dwordx4 v222, v[196:199], s[22:23] offset:256 sc1
	s_nop 1
	global_load_dwordx4 v[196:199], v226, s[24:25] offset:256 nt
	global_load_dwordx4 v[200:203], v226, s[14:15] offset:256 nt
	s_waitcnt vmcnt(20)
	v_cvt_f32_f16_e32 v228, v204
	v_cvt_f32_f16_sdwa v229, v204 dst_sel:DWORD dst_unused:UNUSED_PAD src0_sel:WORD_1
	v_cvt_f32_f16_e32 v230, v205
	v_cvt_f32_f16_sdwa v231, v205 dst_sel:DWORD dst_unused:UNUSED_PAD src0_sel:WORD_1
	v_cvt_f32_f16_e32 v232, v206
	v_cvt_f32_f16_sdwa v233, v206 dst_sel:DWORD dst_unused:UNUSED_PAD src0_sel:WORD_1
	v_cvt_f32_f16_e32 v234, v207
	v_cvt_f32_f16_sdwa v235, v207 dst_sel:DWORD dst_unused:UNUSED_PAD src0_sel:WORD_1
	v_cvt_f32_f16_e32 v236, v208
	v_cvt_f32_f16_sdwa v237, v208 dst_sel:DWORD dst_unused:UNUSED_PAD src0_sel:WORD_1
	v_cvt_f32_f16_e32 v238, v209
	v_cvt_f32_f16_sdwa v239, v209 dst_sel:DWORD dst_unused:UNUSED_PAD src0_sel:WORD_1
	v_cvt_f32_f16_e32 v240, v210
	v_cvt_f32_f16_sdwa v241, v210 dst_sel:DWORD dst_unused:UNUSED_PAD src0_sel:WORD_1
	v_cvt_f32_f16_e32 v242, v211
	v_cvt_f32_f16_sdwa v243, v211 dst_sel:DWORD dst_unused:UNUSED_PAD src0_sel:WORD_1
	v_pk_fma_f32 v[76:77], v[76:77], v[236:237], v[228:229]
	v_pk_fma_f32 v[78:79], v[78:79], v[238:239], v[230:231]
	v_pk_fma_f32 v[72:73], v[72:73], v[240:241], v[232:233]
	v_pk_fma_f32 v[74:75], v[74:75], v[242:243], v[234:235]
	v_cvt_pk_f16_f32 v204, v76, v77
	v_cvt_pk_f16_f32 v205, v78, v79
	v_cvt_pk_f16_f32 v206, v72, v73
	v_cvt_pk_f16_f32 v207, v74, v75
	global_store_dwordx4 v223, v[204:207], s[22:23] sc1
	s_nop 1
	global_load_dwordx4 v[204:207], v227, s[24:25] nt
	global_load_dwordx4 v[208:211], v227, s[14:15] nt
	s_waitcnt vmcnt(21)
	v_cvt_f32_f16_e32 v228, v212
	v_cvt_f32_f16_sdwa v229, v212 dst_sel:DWORD dst_unused:UNUSED_PAD src0_sel:WORD_1
	v_cvt_f32_f16_e32 v230, v213
	v_cvt_f32_f16_sdwa v231, v213 dst_sel:DWORD dst_unused:UNUSED_PAD src0_sel:WORD_1
	v_cvt_f32_f16_e32 v232, v214
	v_cvt_f32_f16_sdwa v233, v214 dst_sel:DWORD dst_unused:UNUSED_PAD src0_sel:WORD_1
	v_cvt_f32_f16_e32 v234, v215
	v_cvt_f32_f16_sdwa v235, v215 dst_sel:DWORD dst_unused:UNUSED_PAD src0_sel:WORD_1
	v_cvt_f32_f16_e32 v236, v216
	v_cvt_f32_f16_sdwa v237, v216 dst_sel:DWORD dst_unused:UNUSED_PAD src0_sel:WORD_1
	v_cvt_f32_f16_e32 v238, v217
	v_cvt_f32_f16_sdwa v239, v217 dst_sel:DWORD dst_unused:UNUSED_PAD src0_sel:WORD_1
	v_cvt_f32_f16_e32 v240, v218
	v_cvt_f32_f16_sdwa v241, v218 dst_sel:DWORD dst_unused:UNUSED_PAD src0_sel:WORD_1
	v_cvt_f32_f16_e32 v242, v219
	v_cvt_f32_f16_sdwa v243, v219 dst_sel:DWORD dst_unused:UNUSED_PAD src0_sel:WORD_1
	v_pk_fma_f32 v[68:69], v[68:69], v[236:237], v[228:229]
	v_pk_fma_f32 v[70:71], v[70:71], v[238:239], v[230:231]
	v_pk_fma_f32 v[64:65], v[64:65], v[240:241], v[232:233]
	v_pk_fma_f32 v[66:67], v[66:67], v[242:243], v[234:235]
	v_cvt_pk_f16_f32 v212, v68, v69
	v_cvt_pk_f16_f32 v213, v70, v71
	v_cvt_pk_f16_f32 v214, v64, v65
	v_cvt_pk_f16_f32 v215, v66, v67
	global_store_dwordx4 v223, v[212:215], s[22:23] offset:256 sc1
	s_nop 1
	global_load_dwordx4 v[212:215], v227, s[24:25] offset:256 nt
	global_load_dwordx4 v[216:219], v227, s[14:15] offset:256 nt
	s_waitcnt vmcnt(21)
	v_cvt_f32_f16_e32 v228, v156
	v_cvt_f32_f16_sdwa v229, v156 dst_sel:DWORD dst_unused:UNUSED_PAD src0_sel:WORD_1
	v_cvt_f32_f16_e32 v230, v157
	v_cvt_f32_f16_sdwa v231, v157 dst_sel:DWORD dst_unused:UNUSED_PAD src0_sel:WORD_1
	v_cvt_f32_f16_e32 v232, v158
	v_cvt_f32_f16_sdwa v233, v158 dst_sel:DWORD dst_unused:UNUSED_PAD src0_sel:WORD_1
	v_cvt_f32_f16_e32 v234, v159
	v_cvt_f32_f16_sdwa v235, v159 dst_sel:DWORD dst_unused:UNUSED_PAD src0_sel:WORD_1
	v_cvt_f32_f16_e32 v236, v160
	v_cvt_f32_f16_sdwa v237, v160 dst_sel:DWORD dst_unused:UNUSED_PAD src0_sel:WORD_1
	v_cvt_f32_f16_e32 v238, v161
	v_cvt_f32_f16_sdwa v239, v161 dst_sel:DWORD dst_unused:UNUSED_PAD src0_sel:WORD_1
	v_cvt_f32_f16_e32 v240, v162
	v_cvt_f32_f16_sdwa v241, v162 dst_sel:DWORD dst_unused:UNUSED_PAD src0_sel:WORD_1
	v_cvt_f32_f16_e32 v242, v163
	v_cvt_f32_f16_sdwa v243, v163 dst_sel:DWORD dst_unused:UNUSED_PAD src0_sel:WORD_1
	v_pk_fma_f32 v[60:61], v[60:61], v[236:237], v[228:229]
	v_pk_fma_f32 v[62:63], v[62:63], v[238:239], v[230:231]
	v_pk_fma_f32 v[56:57], v[56:57], v[240:241], v[232:233]
	v_pk_fma_f32 v[58:59], v[58:59], v[242:243], v[234:235]
	v_cvt_pk_f16_f32 v156, v60, v61
	v_cvt_pk_f16_f32 v157, v62, v63
	v_cvt_pk_f16_f32 v158, v56, v57
	v_cvt_pk_f16_f32 v159, v58, v59
	global_store_dwordx4 v224, v[156:159], s[22:23] sc1
	s_nop 1
	s_waitcnt vmcnt(19)
	v_cvt_f32_f16_e32 v228, v164
	v_cvt_f32_f16_sdwa v229, v164 dst_sel:DWORD dst_unused:UNUSED_PAD src0_sel:WORD_1
	v_cvt_f32_f16_e32 v230, v165
	v_cvt_f32_f16_sdwa v231, v165 dst_sel:DWORD dst_unused:UNUSED_PAD src0_sel:WORD_1
	v_cvt_f32_f16_e32 v232, v166
	v_cvt_f32_f16_sdwa v233, v166 dst_sel:DWORD dst_unused:UNUSED_PAD src0_sel:WORD_1
	v_cvt_f32_f16_e32 v234, v167
	v_cvt_f32_f16_sdwa v235, v167 dst_sel:DWORD dst_unused:UNUSED_PAD src0_sel:WORD_1
	v_cvt_f32_f16_e32 v236, v168
	v_cvt_f32_f16_sdwa v237, v168 dst_sel:DWORD dst_unused:UNUSED_PAD src0_sel:WORD_1
	v_cvt_f32_f16_e32 v238, v169
	v_cvt_f32_f16_sdwa v239, v169 dst_sel:DWORD dst_unused:UNUSED_PAD src0_sel:WORD_1
	v_cvt_f32_f16_e32 v240, v170
	v_cvt_f32_f16_sdwa v241, v170 dst_sel:DWORD dst_unused:UNUSED_PAD src0_sel:WORD_1
	v_cvt_f32_f16_e32 v242, v171
	v_cvt_f32_f16_sdwa v243, v171 dst_sel:DWORD dst_unused:UNUSED_PAD src0_sel:WORD_1
	v_pk_fma_f32 v[52:53], v[52:53], v[236:237], v[228:229]
	v_pk_fma_f32 v[54:55], v[54:55], v[238:239], v[230:231]
	v_pk_fma_f32 v[48:49], v[48:49], v[240:241], v[232:233]
	v_pk_fma_f32 v[50:51], v[50:51], v[242:243], v[234:235]
	v_cvt_pk_f16_f32 v164, v52, v53
	v_cvt_pk_f16_f32 v165, v54, v55
	v_cvt_pk_f16_f32 v166, v48, v49
	v_cvt_pk_f16_f32 v167, v50, v51
	global_store_dwordx4 v224, v[164:167], s[22:23] offset:256 sc1
	s_nop 1
	s_waitcnt vmcnt(17)
	v_cvt_f32_f16_e32 v228, v172
	v_cvt_f32_f16_sdwa v229, v172 dst_sel:DWORD dst_unused:UNUSED_PAD src0_sel:WORD_1
	v_cvt_f32_f16_e32 v230, v173
	v_cvt_f32_f16_sdwa v231, v173 dst_sel:DWORD dst_unused:UNUSED_PAD src0_sel:WORD_1
	v_cvt_f32_f16_e32 v232, v174
	v_cvt_f32_f16_sdwa v233, v174 dst_sel:DWORD dst_unused:UNUSED_PAD src0_sel:WORD_1
	v_cvt_f32_f16_e32 v234, v175
	v_cvt_f32_f16_sdwa v235, v175 dst_sel:DWORD dst_unused:UNUSED_PAD src0_sel:WORD_1
	v_cvt_f32_f16_e32 v236, v176
	v_cvt_f32_f16_sdwa v237, v176 dst_sel:DWORD dst_unused:UNUSED_PAD src0_sel:WORD_1
	v_cvt_f32_f16_e32 v238, v177
	v_cvt_f32_f16_sdwa v239, v177 dst_sel:DWORD dst_unused:UNUSED_PAD src0_sel:WORD_1
	v_cvt_f32_f16_e32 v240, v178
	v_cvt_f32_f16_sdwa v241, v178 dst_sel:DWORD dst_unused:UNUSED_PAD src0_sel:WORD_1
	v_cvt_f32_f16_e32 v242, v179
	v_cvt_f32_f16_sdwa v243, v179 dst_sel:DWORD dst_unused:UNUSED_PAD src0_sel:WORD_1
	v_pk_fma_f32 v[44:45], v[44:45], v[236:237], v[228:229]
	v_pk_fma_f32 v[46:47], v[46:47], v[238:239], v[230:231]
	v_pk_fma_f32 v[40:41], v[40:41], v[240:241], v[232:233]
	v_pk_fma_f32 v[42:43], v[42:43], v[242:243], v[234:235]
	v_cvt_pk_f16_f32 v172, v44, v45
	v_cvt_pk_f16_f32 v173, v46, v47
	v_cvt_pk_f16_f32 v174, v40, v41
	v_cvt_pk_f16_f32 v175, v42, v43
	global_store_dwordx4 v225, v[172:175], s[22:23] sc1
	s_nop 1
	s_waitcnt vmcnt(15)
	v_cvt_f32_f16_e32 v228, v180
	v_cvt_f32_f16_sdwa v229, v180 dst_sel:DWORD dst_unused:UNUSED_PAD src0_sel:WORD_1
	v_cvt_f32_f16_e32 v230, v181
	v_cvt_f32_f16_sdwa v231, v181 dst_sel:DWORD dst_unused:UNUSED_PAD src0_sel:WORD_1
	v_cvt_f32_f16_e32 v232, v182
	v_cvt_f32_f16_sdwa v233, v182 dst_sel:DWORD dst_unused:UNUSED_PAD src0_sel:WORD_1
	v_cvt_f32_f16_e32 v234, v183
	v_cvt_f32_f16_sdwa v235, v183 dst_sel:DWORD dst_unused:UNUSED_PAD src0_sel:WORD_1
	v_cvt_f32_f16_e32 v236, v184
	v_cvt_f32_f16_sdwa v237, v184 dst_sel:DWORD dst_unused:UNUSED_PAD src0_sel:WORD_1
	v_cvt_f32_f16_e32 v238, v185
	v_cvt_f32_f16_sdwa v239, v185 dst_sel:DWORD dst_unused:UNUSED_PAD src0_sel:WORD_1
	v_cvt_f32_f16_e32 v240, v186
	v_cvt_f32_f16_sdwa v241, v186 dst_sel:DWORD dst_unused:UNUSED_PAD src0_sel:WORD_1
	v_cvt_f32_f16_e32 v242, v187
	v_cvt_f32_f16_sdwa v243, v187 dst_sel:DWORD dst_unused:UNUSED_PAD src0_sel:WORD_1
	v_pk_fma_f32 v[36:37], v[36:37], v[236:237], v[228:229]
	v_pk_fma_f32 v[38:39], v[38:39], v[238:239], v[230:231]
	v_pk_fma_f32 v[32:33], v[32:33], v[240:241], v[232:233]
	v_pk_fma_f32 v[34:35], v[34:35], v[242:243], v[234:235]
	v_cvt_pk_f16_f32 v180, v36, v37
	v_cvt_pk_f16_f32 v181, v38, v39
	v_cvt_pk_f16_f32 v182, v32, v33
	v_cvt_pk_f16_f32 v183, v34, v35
	global_store_dwordx4 v225, v[180:183], s[22:23] offset:256 sc1
	s_nop 1
	s_waitcnt vmcnt(13)
	v_cvt_f32_f16_e32 v228, v188
	v_cvt_f32_f16_sdwa v229, v188 dst_sel:DWORD dst_unused:UNUSED_PAD src0_sel:WORD_1
	v_cvt_f32_f16_e32 v230, v189
	v_cvt_f32_f16_sdwa v231, v189 dst_sel:DWORD dst_unused:UNUSED_PAD src0_sel:WORD_1
	v_cvt_f32_f16_e32 v232, v190
	v_cvt_f32_f16_sdwa v233, v190 dst_sel:DWORD dst_unused:UNUSED_PAD src0_sel:WORD_1
	v_cvt_f32_f16_e32 v234, v191
	v_cvt_f32_f16_sdwa v235, v191 dst_sel:DWORD dst_unused:UNUSED_PAD src0_sel:WORD_1
	v_cvt_f32_f16_e32 v236, v192
	v_cvt_f32_f16_sdwa v237, v192 dst_sel:DWORD dst_unused:UNUSED_PAD src0_sel:WORD_1
	v_cvt_f32_f16_e32 v238, v193
	v_cvt_f32_f16_sdwa v239, v193 dst_sel:DWORD dst_unused:UNUSED_PAD src0_sel:WORD_1
	v_cvt_f32_f16_e32 v240, v194
	v_cvt_f32_f16_sdwa v241, v194 dst_sel:DWORD dst_unused:UNUSED_PAD src0_sel:WORD_1
	v_cvt_f32_f16_e32 v242, v195
	v_cvt_f32_f16_sdwa v243, v195 dst_sel:DWORD dst_unused:UNUSED_PAD src0_sel:WORD_1
	v_pk_fma_f32 v[28:29], v[28:29], v[236:237], v[228:229]
	v_pk_fma_f32 v[30:31], v[30:31], v[238:239], v[230:231]
	v_pk_fma_f32 v[24:25], v[24:25], v[240:241], v[232:233]
	v_pk_fma_f32 v[26:27], v[26:27], v[242:243], v[234:235]
	v_cvt_pk_f16_f32 v188, v28, v29
	v_cvt_pk_f16_f32 v189, v30, v31
	v_cvt_pk_f16_f32 v190, v24, v25
	v_cvt_pk_f16_f32 v191, v26, v27
	global_store_dwordx4 v226, v[188:191], s[22:23] sc1
	s_nop 1
	s_waitcnt vmcnt(11)
	v_cvt_f32_f16_e32 v228, v196
	v_cvt_f32_f16_sdwa v229, v196 dst_sel:DWORD dst_unused:UNUSED_PAD src0_sel:WORD_1
	v_cvt_f32_f16_e32 v230, v197
	v_cvt_f32_f16_sdwa v231, v197 dst_sel:DWORD dst_unused:UNUSED_PAD src0_sel:WORD_1
	v_cvt_f32_f16_e32 v232, v198
	v_cvt_f32_f16_sdwa v233, v198 dst_sel:DWORD dst_unused:UNUSED_PAD src0_sel:WORD_1
	v_cvt_f32_f16_e32 v234, v199
	v_cvt_f32_f16_sdwa v235, v199 dst_sel:DWORD dst_unused:UNUSED_PAD src0_sel:WORD_1
	v_cvt_f32_f16_e32 v236, v200
	v_cvt_f32_f16_sdwa v237, v200 dst_sel:DWORD dst_unused:UNUSED_PAD src0_sel:WORD_1
	v_cvt_f32_f16_e32 v238, v201
	v_cvt_f32_f16_sdwa v239, v201 dst_sel:DWORD dst_unused:UNUSED_PAD src0_sel:WORD_1
	v_cvt_f32_f16_e32 v240, v202
	v_cvt_f32_f16_sdwa v241, v202 dst_sel:DWORD dst_unused:UNUSED_PAD src0_sel:WORD_1
	v_cvt_f32_f16_e32 v242, v203
	v_cvt_f32_f16_sdwa v243, v203 dst_sel:DWORD dst_unused:UNUSED_PAD src0_sel:WORD_1
	v_pk_fma_f32 v[20:21], v[20:21], v[236:237], v[228:229]
	v_pk_fma_f32 v[22:23], v[22:23], v[238:239], v[230:231]
	v_pk_fma_f32 v[16:17], v[16:17], v[240:241], v[232:233]
	v_pk_fma_f32 v[18:19], v[18:19], v[242:243], v[234:235]
	v_cvt_pk_f16_f32 v196, v20, v21
	v_cvt_pk_f16_f32 v197, v22, v23
	v_cvt_pk_f16_f32 v198, v16, v17
	v_cvt_pk_f16_f32 v199, v18, v19
	global_store_dwordx4 v226, v[196:199], s[22:23] offset:256 sc1
	s_nop 1
	s_waitcnt vmcnt(9)
	v_cvt_f32_f16_e32 v228, v204
	v_cvt_f32_f16_sdwa v229, v204 dst_sel:DWORD dst_unused:UNUSED_PAD src0_sel:WORD_1
	v_cvt_f32_f16_e32 v230, v205
	v_cvt_f32_f16_sdwa v231, v205 dst_sel:DWORD dst_unused:UNUSED_PAD src0_sel:WORD_1
	v_cvt_f32_f16_e32 v232, v206
	v_cvt_f32_f16_sdwa v233, v206 dst_sel:DWORD dst_unused:UNUSED_PAD src0_sel:WORD_1
	v_cvt_f32_f16_e32 v234, v207
	v_cvt_f32_f16_sdwa v235, v207 dst_sel:DWORD dst_unused:UNUSED_PAD src0_sel:WORD_1
	v_cvt_f32_f16_e32 v236, v208
	v_cvt_f32_f16_sdwa v237, v208 dst_sel:DWORD dst_unused:UNUSED_PAD src0_sel:WORD_1
	v_cvt_f32_f16_e32 v238, v209
	v_cvt_f32_f16_sdwa v239, v209 dst_sel:DWORD dst_unused:UNUSED_PAD src0_sel:WORD_1
	v_cvt_f32_f16_e32 v240, v210
	v_cvt_f32_f16_sdwa v241, v210 dst_sel:DWORD dst_unused:UNUSED_PAD src0_sel:WORD_1
	v_cvt_f32_f16_e32 v242, v211
	v_cvt_f32_f16_sdwa v243, v211 dst_sel:DWORD dst_unused:UNUSED_PAD src0_sel:WORD_1
	v_pk_fma_f32 v[12:13], v[12:13], v[236:237], v[228:229]
	v_pk_fma_f32 v[14:15], v[14:15], v[238:239], v[230:231]
	v_pk_fma_f32 v[8:9], v[8:9], v[240:241], v[232:233]
	v_pk_fma_f32 v[10:11], v[10:11], v[242:243], v[234:235]
	v_cvt_pk_f16_f32 v204, v12, v13
	v_cvt_pk_f16_f32 v205, v14, v15
	v_cvt_pk_f16_f32 v206, v8, v9
	v_cvt_pk_f16_f32 v207, v10, v11
	global_store_dwordx4 v227, v[204:207], s[22:23] sc1
	s_nop 1
	s_waitcnt vmcnt(7)
	v_cvt_f32_f16_e32 v228, v212
	v_cvt_f32_f16_sdwa v229, v212 dst_sel:DWORD dst_unused:UNUSED_PAD src0_sel:WORD_1
	v_cvt_f32_f16_e32 v230, v213
	v_cvt_f32_f16_sdwa v231, v213 dst_sel:DWORD dst_unused:UNUSED_PAD src0_sel:WORD_1
	v_cvt_f32_f16_e32 v232, v214
	v_cvt_f32_f16_sdwa v233, v214 dst_sel:DWORD dst_unused:UNUSED_PAD src0_sel:WORD_1
	v_cvt_f32_f16_e32 v234, v215
	v_cvt_f32_f16_sdwa v235, v215 dst_sel:DWORD dst_unused:UNUSED_PAD src0_sel:WORD_1
	v_cvt_f32_f16_e32 v236, v216
	v_cvt_f32_f16_sdwa v237, v216 dst_sel:DWORD dst_unused:UNUSED_PAD src0_sel:WORD_1
	v_cvt_f32_f16_e32 v238, v217
	v_cvt_f32_f16_sdwa v239, v217 dst_sel:DWORD dst_unused:UNUSED_PAD src0_sel:WORD_1
	v_cvt_f32_f16_e32 v240, v218
	v_cvt_f32_f16_sdwa v241, v218 dst_sel:DWORD dst_unused:UNUSED_PAD src0_sel:WORD_1
	v_cvt_f32_f16_e32 v242, v219
	v_cvt_f32_f16_sdwa v243, v219 dst_sel:DWORD dst_unused:UNUSED_PAD src0_sel:WORD_1
	v_pk_fma_f32 v[4:5], v[4:5], v[236:237], v[228:229]
	v_pk_fma_f32 v[6:7], v[6:7], v[238:239], v[230:231]
	v_pk_fma_f32 v[0:1], v[0:1], v[240:241], v[232:233]
	v_pk_fma_f32 v[2:3], v[2:3], v[242:243], v[234:235]
	v_cvt_pk_f16_f32 v212, v4, v5
	v_cvt_pk_f16_f32 v213, v6, v7
	v_cvt_pk_f16_f32 v214, v0, v1
	v_cvt_pk_f16_f32 v215, v2, v3
	global_store_dwordx4 v227, v[212:215], s[22:23] offset:256 sc1
	s_nop 1
	s_waitcnt vmcnt(0)
	s_barrier
	v_mbcnt_lo_u32_b32 v0, -1, 0
	v_mbcnt_hi_u32_b32 v0, -1, v0
	s_nop 0
	v_or_b32_e32 v0, s97, v0
	v_cmp_eq_u32_e32 vcc, 0, v0
	s_and_saveexec_b64 s[10:11], vcc
	s_cbranch_execz .LBB0_1199
	s_mov_b64 s[14:15], exec
	v_mbcnt_lo_u32_b32 v0, s14, 0
	v_mbcnt_hi_u32_b32 v0, s15, v0
	v_cmp_eq_u32_e32 vcc, 0, v0
	s_and_saveexec_b64 s[12:13], vcc
	s_cbranch_execz .LBB0_1238
	s_lshl_b32 s4, s4, 6
	s_lshl_b64 s[16:17], s[4:5], 2
	s_add_u32 s16, s56, s16
	s_addc_u32 s17, s57, s17
	s_bcnt1_i32_b64 s4, s[14:15]
	v_mov_b32_e32 v0, s4
	global_atomic_add v129, v0, s[16:17]
